# PEER partial sums ph stored [token][slice][128] instead of [slice][token][128]: the 8 slice reads of the combine phase sit in one 4 KiB block (immediate offsets, no 32 MiB-strided streams)
# speedup vs baseline: 1.0553x; 1.0031x over previous
; DI float dot16(const unsigned (&a)[8], u32x4 b0, u32x4 b1) {
;     float acc;
;     asm volatile("v_dot2_f32_bf16 %0, %1, %9, 0\n\tv_dot2_f32_bf16 %0, %2, %10, %0\n\tv_dot2_f32_bf16 %0, %3, %11, %0\n\tv_dot2_f32_bf16 %0, %4, %12, %0\n\t"
;                  "v_dot2_f32_bf16 %0, %5, %13, %0\n\tv_dot2_f32_bf16 %0, %6, %14, %0\n\tv_dot2_f32_bf16 %0, %7, %15, %0\n\tv_dot2_f32_bf16 %0, %8, %16, %0\n\ts_nop 2"
;                  : "=&v"(acc)
;                  : "v"(a[0]), "v"(a[1]), "v"(a[2]), "v"(a[3]), "v"(a[4]), "v"(a[5]), "v"(a[6]), "v"(a[7]),
;                    "v"(b0.x), "v"(b0.y), "v"(b0.z), "v"(b0.w), "v"(b1.x), "v"(b1.y), "v"(b1.z), "v"(b1.w));
;     return acc;
; }
; DI float dot_fp8_row(u32x4 u, u32x4 xa, u32x4 xb) {
;     unsigned a[8];
; #pragma unroll
;     for (int j = 0; j < 4; ++j) {
;         a[2 * j] = __builtin_bit_cast(unsigned, __builtin_amdgcn_cvt_scalef32_pk_bf16_fp8(u[j], 1.0f, false));
;         a[2 * j + 1] = __builtin_bit_cast(unsigned, __builtin_amdgcn_cvt_scalef32_pk_bf16_fp8(u[j], 1.0f, true));
;     }
;     return dot16(a, xa, xb);
; }
.LBB0_528:
	s_or_b64 exec, exec, s[0:1]
	s_lshl_b32 s56, s27, 9
	v_lshl_add_u64 v[184:185], v[166:167], 0, s[56:57]
	s_mov_b64 s[72:73], 0
	v_mov_b32_e32 v188, v152
	s_branch .LBB0_531
.LBB0_529:
	s_or_b64 exec, exec, s[18:19]
	s_setprio 1
	v_cvt_scalef32_pk_bf16_fp8 v190, v7, 1.0
	v_cvt_scalef32_pk_bf16_fp8 v188, v6, 1.0
	v_cvt_scalef32_pk_bf16_fp8 v189, v6, 1.0 op_sel:[1,0,0]
	v_cvt_scalef32_pk_bf16_fp8 v191, v7, 1.0 op_sel:[1,0,0]
	v_cvt_scalef32_pk_bf16_fp8 v211, v8, 1.0
	v_cvt_scalef32_pk_bf16_fp8 v212, v8, 1.0 op_sel:[1,0,0]
	v_cvt_scalef32_pk_bf16_fp8 v213, v9, 1.0
	v_cvt_scalef32_pk_bf16_fp8 v214, v9, 1.0 op_sel:[1,0,0]
	v_dot2_f32_bf16 v215, v188, v66, 0
	v_dot2_f32_bf16 v215, v189, v67, v215
	v_dot2_f32_bf16 v215, v190, v68, v215
	v_dot2_f32_bf16 v215, v191, v69, v215
	v_dot2_f32_bf16 v215, v211, v70, v215
	v_dot2_f32_bf16 v215, v212, v71, v215
	v_dot2_f32_bf16 v215, v213, v72, v215
	v_dot2_f32_bf16 v215, v214, v73, v215
	s_nop 2
	v_cvt_scalef32_pk_bf16_fp8 v190, v3, 1.0
	v_cvt_scalef32_pk_bf16_fp8 v188, v2, 1.0
	v_cvt_scalef32_pk_bf16_fp8 v189, v2, 1.0 op_sel:[1,0,0]
	v_cvt_scalef32_pk_bf16_fp8 v191, v3, 1.0 op_sel:[1,0,0]
	v_cvt_scalef32_pk_bf16_fp8 v211, v4, 1.0
	v_cvt_scalef32_pk_bf16_fp8 v212, v4, 1.0 op_sel:[1,0,0]
	v_cvt_scalef32_pk_bf16_fp8 v213, v5, 1.0
	v_cvt_scalef32_pk_bf16_fp8 v214, v5, 1.0 op_sel:[1,0,0]
	v_dot2_f32_bf16 v216, v188, v66, 0
	v_dot2_f32_bf16 v216, v189, v67, v216
	v_dot2_f32_bf16 v216, v190, v68, v216
	v_dot2_f32_bf16 v216, v191, v69, v216
	v_dot2_f32_bf16 v216, v211, v70, v216
	v_dot2_f32_bf16 v216, v212, v71, v216
	v_dot2_f32_bf16 v216, v213, v72, v216
	v_dot2_f32_bf16 v216, v214, v73, v216
	s_nop 2
	v_cvt_scalef32_pk_bf16_fp8 v190, v15, 1.0
	v_cvt_scalef32_pk_bf16_fp8 v188, v14, 1.0
	v_cvt_scalef32_pk_bf16_fp8 v189, v14, 1.0 op_sel:[1,0,0]
	v_cvt_scalef32_pk_bf16_fp8 v191, v15, 1.0 op_sel:[1,0,0]
	v_cvt_scalef32_pk_bf16_fp8 v211, v16, 1.0
	v_cvt_scalef32_pk_bf16_fp8 v212, v16, 1.0 op_sel:[1,0,0]
	v_cvt_scalef32_pk_bf16_fp8 v213, v17, 1.0
	v_cvt_scalef32_pk_bf16_fp8 v214, v17, 1.0 op_sel:[1,0,0]
	v_dot2_f32_bf16 v217, v188, v66, 0
	v_dot2_f32_bf16 v217, v189, v67, v217
	v_dot2_f32_bf16 v217, v190, v68, v217
	v_dot2_f32_bf16 v217, v191, v69, v217
	v_dot2_f32_bf16 v217, v211, v70, v217
	v_dot2_f32_bf16 v217, v212, v71, v217
	v_dot2_f32_bf16 v217, v213, v72, v217
	v_dot2_f32_bf16 v217, v214, v73, v217
	s_nop 2
	v_cvt_scalef32_pk_bf16_fp8 v190, v11, 1.0
	v_cvt_scalef32_pk_bf16_fp8 v188, v10, 1.0
	v_cvt_scalef32_pk_bf16_fp8 v189, v10, 1.0 op_sel:[1,0,0]
	v_cvt_scalef32_pk_bf16_fp8 v191, v11, 1.0 op_sel:[1,0,0]
	v_cvt_scalef32_pk_bf16_fp8 v211, v12, 1.0
	v_cvt_scalef32_pk_bf16_fp8 v212, v12, 1.0 op_sel:[1,0,0]
	v_cvt_scalef32_pk_bf16_fp8 v213, v13, 1.0
	v_cvt_scalef32_pk_bf16_fp8 v214, v13, 1.0 op_sel:[1,0,0]
	v_dot2_f32_bf16 v218, v188, v66, 0
	v_dot2_f32_bf16 v218, v189, v67, v218
	v_dot2_f32_bf16 v218, v190, v68, v218
	v_dot2_f32_bf16 v218, v191, v69, v218
	v_dot2_f32_bf16 v218, v211, v70, v218
	v_dot2_f32_bf16 v218, v212, v71, v218
	v_dot2_f32_bf16 v218, v213, v72, v218
	v_dot2_f32_bf16 v218, v214, v73, v218
	s_nop 2
	v_cvt_scalef32_pk_bf16_fp8 v190, v23, 1.0
	v_cvt_scalef32_pk_bf16_fp8 v188, v22, 1.0
	v_cvt_scalef32_pk_bf16_fp8 v189, v22, 1.0 op_sel:[1,0,0]
	v_cvt_scalef32_pk_bf16_fp8 v191, v23, 1.0 op_sel:[1,0,0]
	v_cvt_scalef32_pk_bf16_fp8 v211, v24, 1.0
	v_cvt_scalef32_pk_bf16_fp8 v212, v24, 1.0 op_sel:[1,0,0]
	v_cvt_scalef32_pk_bf16_fp8 v213, v25, 1.0
	v_cvt_scalef32_pk_bf16_fp8 v214, v25, 1.0 op_sel:[1,0,0]
	v_dot2_f32_bf16 v219, v188, v66, 0
	v_dot2_f32_bf16 v219, v189, v67, v219
	v_dot2_f32_bf16 v219, v190, v68, v219
	v_dot2_f32_bf16 v219, v191, v69, v219
	v_dot2_f32_bf16 v219, v211, v70, v219
	v_dot2_f32_bf16 v219, v212, v71, v219
	v_dot2_f32_bf16 v219, v213, v72, v219
	v_dot2_f32_bf16 v219, v214, v73, v219
	s_nop 2
	v_cvt_scalef32_pk_bf16_fp8 v190, v19, 1.0
	v_cvt_scalef32_pk_bf16_fp8 v188, v18, 1.0
	v_cvt_scalef32_pk_bf16_fp8 v189, v18, 1.0 op_sel:[1,0,0]
	v_cvt_scalef32_pk_bf16_fp8 v191, v19, 1.0 op_sel:[1,0,0]
	v_cvt_scalef32_pk_bf16_fp8 v211, v20, 1.0
	v_cvt_scalef32_pk_bf16_fp8 v212, v20, 1.0 op_sel:[1,0,0]
	v_cvt_scalef32_pk_bf16_fp8 v213, v21, 1.0
	v_cvt_scalef32_pk_bf16_fp8 v214, v21, 1.0 op_sel:[1,0,0]
	v_dot2_f32_bf16 v220, v188, v66, 0
	v_dot2_f32_bf16 v220, v189, v67, v220
	v_dot2_f32_bf16 v220, v190, v68, v220
	v_dot2_f32_bf16 v220, v191, v69, v220
	v_dot2_f32_bf16 v220, v211, v70, v220
	v_dot2_f32_bf16 v220, v212, v71, v220
	v_dot2_f32_bf16 v220, v213, v72, v220
	v_dot2_f32_bf16 v220, v214, v73, v220
	s_nop 2
	v_cvt_scalef32_pk_bf16_fp8 v190, v31, 1.0
	v_cvt_scalef32_pk_bf16_fp8 v188, v30, 1.0
	v_cvt_scalef32_pk_bf16_fp8 v189, v30, 1.0 op_sel:[1,0,0]
	v_cvt_scalef32_pk_bf16_fp8 v191, v31, 1.0 op_sel:[1,0,0]
	v_cvt_scalef32_pk_bf16_fp8 v211, v32, 1.0
	v_cvt_scalef32_pk_bf16_fp8 v212, v32, 1.0 op_sel:[1,0,0]
	v_cvt_scalef32_pk_bf16_fp8 v213, v33, 1.0
	v_cvt_scalef32_pk_bf16_fp8 v214, v33, 1.0 op_sel:[1,0,0]
	v_dot2_f32_bf16 v221, v188, v66, 0
	v_dot2_f32_bf16 v221, v189, v67, v221
	v_dot2_f32_bf16 v221, v190, v68, v221
	v_dot2_f32_bf16 v221, v191, v69, v221
	v_dot2_f32_bf16 v221, v211, v70, v221
	v_dot2_f32_bf16 v221, v212, v71, v221
	v_dot2_f32_bf16 v221, v213, v72, v221
	v_dot2_f32_bf16 v221, v214, v73, v221
	s_nop 2
	v_cvt_scalef32_pk_bf16_fp8 v190, v27, 1.0
	v_cvt_scalef32_pk_bf16_fp8 v188, v26, 1.0
	v_cvt_scalef32_pk_bf16_fp8 v189, v26, 1.0 op_sel:[1,0,0]
	v_cvt_scalef32_pk_bf16_fp8 v191, v27, 1.0 op_sel:[1,0,0]
	v_cvt_scalef32_pk_bf16_fp8 v211, v28, 1.0
	v_cvt_scalef32_pk_bf16_fp8 v212, v28, 1.0 op_sel:[1,0,0]
	v_cvt_scalef32_pk_bf16_fp8 v214, v29, 1.0
	v_cvt_scalef32_pk_bf16_fp8 v222, v29, 1.0 op_sel:[1,0,0]
	v_dot2_f32_bf16 v223, v188, v66, 0
	v_dot2_f32_bf16 v223, v189, v67, v223
	v_dot2_f32_bf16 v223, v190, v68, v223
	v_dot2_f32_bf16 v223, v191, v69, v223
	v_dot2_f32_bf16 v223, v211, v70, v223
	v_dot2_f32_bf16 v223, v212, v71, v223
	v_dot2_f32_bf16 v223, v214, v72, v223
	v_dot2_f32_bf16 v223, v222, v73, v223
	s_nop 2
	v_cndmask_b32_e64 v190, v216, v220, s[12:13]
	ds_bpermute_b32 v190, v193, v190
	v_cndmask_b32_e64 v191, v217, v221, s[12:13]
	v_cndmask_b32_e64 v213, v215, v219, s[12:13]
	ds_bpermute_b32 v191, v193, v191
	v_cndmask_b32_e64 v211, v218, v223, s[12:13]
	ds_bpermute_b32 v213, v193, v213
	ds_bpermute_b32 v211, v193, v211
	v_cndmask_b32_e64 v189, v220, v216, s[12:13]
	s_waitcnt lgkmcnt(3)
; DI float dot16(const unsigned (&a)[8], u32x4 b0, u32x4 b1) {
;     float acc;
;     asm volatile("v_dot2_f32_bf16 %0, %1, %9, 0\n\tv_dot2_f32_bf16 %0, %2, %10, %0\n\tv_dot2_f32_bf16 %0, %3, %11, %0\n\tv_dot2_f32_bf16 %0, %4, %12, %0\n\t"
;                  "v_dot2_f32_bf16 %0, %5, %13, %0\n\tv_dot2_f32_bf16 %0, %6, %14, %0\n\tv_dot2_f32_bf16 %0, %7, %15, %0\n\tv_dot2_f32_bf16 %0, %8, %16, %0\n\ts_nop 2"
;                  : "=&v"(acc)
;                  : "v"(a[0]), "v"(a[1]), "v"(a[2]), "v"(a[3]), "v"(a[4]), "v"(a[5]), "v"(a[6]), "v"(a[7]),
;                    "v"(b0.x), "v"(b0.y), "v"(b0.z), "v"(b0.w), "v"(b1.x), "v"(b1.y), "v"(b1.z), "v"(b1.w));
;     return acc;
; }
; DI float dot_fp8_row(u32x4 u, u32x4 xa, u32x4 xb) {
;     unsigned a[8];
; #pragma unroll
;     for (int j = 0; j < 4; ++j) {
;         a[2 * j] = __builtin_bit_cast(unsigned, __builtin_amdgcn_cvt_scalef32_pk_bf16_fp8(u[j], 1.0f, false));
;         a[2 * j + 1] = __builtin_bit_cast(unsigned, __builtin_amdgcn_cvt_scalef32_pk_bf16_fp8(u[j], 1.0f, true));
;     }
;     return dot16(a, xa, xb);
; }
	v_add_f32_e32 v189, v189, v190
	v_cndmask_b32_e64 v190, v221, v217, s[12:13]
	v_cndmask_b32_e64 v188, v219, v215, s[12:13]
	s_waitcnt lgkmcnt(2)
	v_add_f32_e32 v190, v190, v191
	v_cndmask_b32_e64 v191, v223, v218, s[12:13]
	s_waitcnt lgkmcnt(1)
	v_add_f32_e32 v188, v188, v213
	s_waitcnt lgkmcnt(0)
	v_add_f32_e32 v191, v191, v211
	v_cndmask_b32_e64 v211, v188, v190, s[14:15]
	v_cndmask_b32_e64 v212, v189, v191, s[14:15]
	ds_bpermute_b32 v211, v194, v211
	ds_bpermute_b32 v212, v194, v212
	v_cndmask_b32_e64 v188, v190, v188, s[14:15]
	v_cndmask_b32_e64 v189, v191, v189, s[14:15]
	v_cvt_scalef32_pk_bf16_fp8 v191, v38, 1.0
	s_waitcnt lgkmcnt(1)
	v_add_f32_e32 v188, v188, v211
	s_waitcnt lgkmcnt(0)
	v_add_f32_e32 v189, v189, v212
	v_cvt_scalef32_pk_bf16_fp8 v211, v38, 1.0 op_sel:[1,0,0]
	v_cvt_scalef32_pk_bf16_fp8 v212, v39, 1.0
	v_cvt_scalef32_pk_bf16_fp8 v213, v39, 1.0 op_sel:[1,0,0]
	v_cvt_scalef32_pk_bf16_fp8 v214, v40, 1.0
	v_cvt_scalef32_pk_bf16_fp8 v215, v40, 1.0 op_sel:[1,0,0]
	v_cvt_scalef32_pk_bf16_fp8 v217, v41, 1.0 op_sel:[1,0,0]
	v_cvt_scalef32_pk_bf16_fp8 v216, v41, 1.0
	v_dot2_f32_bf16 v218, v191, v66, 0
	v_dot2_f32_bf16 v218, v211, v67, v218
	v_dot2_f32_bf16 v218, v212, v68, v218
	v_dot2_f32_bf16 v218, v213, v69, v218
	v_dot2_f32_bf16 v218, v214, v70, v218
	v_dot2_f32_bf16 v218, v215, v71, v218
	v_dot2_f32_bf16 v218, v216, v72, v218
	v_dot2_f32_bf16 v218, v217, v73, v218
	s_nop 2
	v_cvt_scalef32_pk_bf16_fp8 v191, v34, 1.0
	v_cvt_scalef32_pk_bf16_fp8 v211, v34, 1.0 op_sel:[1,0,0]
	v_cvt_scalef32_pk_bf16_fp8 v212, v35, 1.0
	v_cvt_scalef32_pk_bf16_fp8 v213, v35, 1.0 op_sel:[1,0,0]
	v_cvt_scalef32_pk_bf16_fp8 v214, v36, 1.0
	v_cvt_scalef32_pk_bf16_fp8 v215, v36, 1.0 op_sel:[1,0,0]
	v_cvt_scalef32_pk_bf16_fp8 v217, v37, 1.0 op_sel:[1,0,0]
	v_cvt_scalef32_pk_bf16_fp8 v216, v37, 1.0
	v_dot2_f32_bf16 v219, v191, v66, 0
	v_dot2_f32_bf16 v219, v211, v67, v219
	v_dot2_f32_bf16 v219, v212, v68, v219
	v_dot2_f32_bf16 v219, v213, v69, v219
	v_dot2_f32_bf16 v219, v214, v70, v219
	v_dot2_f32_bf16 v219, v215, v71, v219
	v_dot2_f32_bf16 v219, v216, v72, v219
	v_dot2_f32_bf16 v219, v217, v73, v219
	s_nop 2
	v_cvt_scalef32_pk_bf16_fp8 v191, v46, 1.0
	v_cvt_scalef32_pk_bf16_fp8 v211, v46, 1.0 op_sel:[1,0,0]
	v_cvt_scalef32_pk_bf16_fp8 v212, v47, 1.0
	v_cvt_scalef32_pk_bf16_fp8 v213, v47, 1.0 op_sel:[1,0,0]
	v_cvt_scalef32_pk_bf16_fp8 v214, v48, 1.0
	v_cvt_scalef32_pk_bf16_fp8 v215, v48, 1.0 op_sel:[1,0,0]
	v_cvt_scalef32_pk_bf16_fp8 v217, v49, 1.0 op_sel:[1,0,0]
	v_cvt_scalef32_pk_bf16_fp8 v216, v49, 1.0
	v_dot2_f32_bf16 v220, v191, v66, 0
	v_dot2_f32_bf16 v220, v211, v67, v220
	v_dot2_f32_bf16 v220, v212, v68, v220
	v_dot2_f32_bf16 v220, v213, v69, v220
	v_dot2_f32_bf16 v220, v214, v70, v220
	v_dot2_f32_bf16 v220, v215, v71, v220
	v_dot2_f32_bf16 v220, v216, v72, v220
	v_dot2_f32_bf16 v220, v217, v73, v220
	s_nop 2
	v_cvt_scalef32_pk_bf16_fp8 v191, v42, 1.0
	v_cvt_scalef32_pk_bf16_fp8 v211, v42, 1.0 op_sel:[1,0,0]
	v_cvt_scalef32_pk_bf16_fp8 v212, v43, 1.0
	v_cvt_scalef32_pk_bf16_fp8 v213, v43, 1.0 op_sel:[1,0,0]
	v_cvt_scalef32_pk_bf16_fp8 v214, v44, 1.0
	v_cvt_scalef32_pk_bf16_fp8 v215, v44, 1.0 op_sel:[1,0,0]
	v_cvt_scalef32_pk_bf16_fp8 v217, v45, 1.0 op_sel:[1,0,0]
	v_cvt_scalef32_pk_bf16_fp8 v216, v45, 1.0
	v_dot2_f32_bf16 v221, v191, v66, 0
	v_dot2_f32_bf16 v221, v211, v67, v221
	v_dot2_f32_bf16 v221, v212, v68, v221
	v_dot2_f32_bf16 v221, v213, v69, v221
	v_dot2_f32_bf16 v221, v214, v70, v221
	v_dot2_f32_bf16 v221, v215, v71, v221
	v_dot2_f32_bf16 v221, v216, v72, v221
	v_dot2_f32_bf16 v221, v217, v73, v221
	s_nop 2
	v_cvt_scalef32_pk_bf16_fp8 v191, v54, 1.0
	v_cvt_scalef32_pk_bf16_fp8 v211, v54, 1.0 op_sel:[1,0,0]
	v_cvt_scalef32_pk_bf16_fp8 v212, v55, 1.0
	v_cvt_scalef32_pk_bf16_fp8 v213, v55, 1.0 op_sel:[1,0,0]
	v_cvt_scalef32_pk_bf16_fp8 v214, v56, 1.0
	v_cvt_scalef32_pk_bf16_fp8 v215, v56, 1.0 op_sel:[1,0,0]
	v_cvt_scalef32_pk_bf16_fp8 v217, v57, 1.0 op_sel:[1,0,0]
	v_cvt_scalef32_pk_bf16_fp8 v216, v57, 1.0
	v_dot2_f32_bf16 v222, v191, v66, 0
	v_dot2_f32_bf16 v222, v211, v67, v222
	v_dot2_f32_bf16 v222, v212, v68, v222
	v_dot2_f32_bf16 v222, v213, v69, v222
	v_dot2_f32_bf16 v222, v214, v70, v222
	v_dot2_f32_bf16 v222, v215, v71, v222
	v_dot2_f32_bf16 v222, v216, v72, v222
	v_dot2_f32_bf16 v222, v217, v73, v222
	s_nop 2
	v_cvt_scalef32_pk_bf16_fp8 v191, v50, 1.0
	v_cvt_scalef32_pk_bf16_fp8 v211, v50, 1.0 op_sel:[1,0,0]
	v_cvt_scalef32_pk_bf16_fp8 v212, v51, 1.0
	v_cvt_scalef32_pk_bf16_fp8 v213, v51, 1.0 op_sel:[1,0,0]
	v_cvt_scalef32_pk_bf16_fp8 v214, v52, 1.0
	v_cvt_scalef32_pk_bf16_fp8 v215, v52, 1.0 op_sel:[1,0,0]
	v_cvt_scalef32_pk_bf16_fp8 v217, v53, 1.0 op_sel:[1,0,0]
	v_cvt_scalef32_pk_bf16_fp8 v216, v53, 1.0
	v_dot2_f32_bf16 v223, v191, v66, 0
	v_dot2_f32_bf16 v223, v211, v67, v223
	v_dot2_f32_bf16 v223, v212, v68, v223
	v_dot2_f32_bf16 v223, v213, v69, v223
	v_dot2_f32_bf16 v223, v214, v70, v223
	v_dot2_f32_bf16 v223, v215, v71, v223
	v_dot2_f32_bf16 v223, v216, v72, v223
	v_dot2_f32_bf16 v223, v217, v73, v223
	s_nop 2
	v_cvt_scalef32_pk_bf16_fp8 v191, v62, 1.0
	v_cvt_scalef32_pk_bf16_fp8 v211, v62, 1.0 op_sel:[1,0,0]
	v_cvt_scalef32_pk_bf16_fp8 v212, v63, 1.0
	v_cvt_scalef32_pk_bf16_fp8 v213, v63, 1.0 op_sel:[1,0,0]
	v_cvt_scalef32_pk_bf16_fp8 v214, v64, 1.0
	v_cvt_scalef32_pk_bf16_fp8 v215, v64, 1.0 op_sel:[1,0,0]
	v_cvt_scalef32_pk_bf16_fp8 v217, v65, 1.0 op_sel:[1,0,0]
	v_cvt_scalef32_pk_bf16_fp8 v216, v65, 1.0
	v_dot2_f32_bf16 v224, v191, v66, 0
	v_dot2_f32_bf16 v224, v211, v67, v224
	v_dot2_f32_bf16 v224, v212, v68, v224
	v_dot2_f32_bf16 v224, v213, v69, v224
	v_dot2_f32_bf16 v224, v214, v70, v224
	v_dot2_f32_bf16 v224, v215, v71, v224
	v_dot2_f32_bf16 v224, v216, v72, v224
	v_dot2_f32_bf16 v224, v217, v73, v224
	s_nop 2
	v_cvt_scalef32_pk_bf16_fp8 v191, v58, 1.0
	v_cvt_scalef32_pk_bf16_fp8 v211, v58, 1.0 op_sel:[1,0,0]
	v_cvt_scalef32_pk_bf16_fp8 v212, v59, 1.0
	v_cvt_scalef32_pk_bf16_fp8 v213, v59, 1.0 op_sel:[1,0,0]
	v_cvt_scalef32_pk_bf16_fp8 v214, v60, 1.0
	v_cvt_scalef32_pk_bf16_fp8 v215, v60, 1.0 op_sel:[1,0,0]
	v_cvt_scalef32_pk_bf16_fp8 v217, v61, 1.0
	v_cvt_scalef32_pk_bf16_fp8 v225, v61, 1.0 op_sel:[1,0,0]
	v_dot2_f32_bf16 v226, v191, v66, 0
	v_dot2_f32_bf16 v226, v211, v67, v226
	v_dot2_f32_bf16 v226, v212, v68, v226
	v_dot2_f32_bf16 v226, v213, v69, v226
	v_dot2_f32_bf16 v226, v214, v70, v226
	v_dot2_f32_bf16 v226, v215, v71, v226
	v_dot2_f32_bf16 v226, v217, v72, v226
	v_dot2_f32_bf16 v226, v225, v73, v226
	s_nop 2
	v_cndmask_b32_e64 v68, v219, v223, s[12:13]
	ds_bpermute_b32 v68, v193, v68
	v_cndmask_b32_e64 v69, v220, v224, s[12:13]
	v_cndmask_b32_e64 v216, v218, v222, s[12:13]
	ds_bpermute_b32 v69, v193, v69
	v_cndmask_b32_e64 v70, v221, v226, s[12:13]
	ds_bpermute_b32 v216, v193, v216
	ds_bpermute_b32 v70, v193, v70
	v_cndmask_b32_e64 v67, v223, v219, s[12:13]
	s_waitcnt lgkmcnt(3)
	v_add_f32_e32 v67, v67, v68
	v_cndmask_b32_e64 v68, v224, v220, s[12:13]
	v_cndmask_b32_e64 v66, v222, v218, s[12:13]
	s_waitcnt lgkmcnt(2)
	v_add_f32_e32 v68, v68, v69
	v_cndmask_b32_e64 v69, v226, v221, s[12:13]
	s_waitcnt lgkmcnt(1)
	v_add_f32_e32 v66, v66, v216
	s_waitcnt lgkmcnt(0)
	v_add_f32_e32 v69, v69, v70
	v_cndmask_b32_e64 v70, v66, v68, s[14:15]
	v_cndmask_b32_e64 v71, v67, v69, s[14:15]
	ds_bpermute_b32 v70, v194, v70
	ds_bpermute_b32 v71, v194, v71
	v_cndmask_b32_e64 v66, v68, v66, s[14:15]
	v_cndmask_b32_e64 v67, v69, v67, s[14:15]
	v_cndmask_b32_e64 v190, v188, v189, s[16:17]
	s_waitcnt lgkmcnt(1)
	v_add_f32_e32 v66, v66, v70
	s_waitcnt lgkmcnt(0)
	v_add_f32_e32 v67, v67, v71
	v_cndmask_b32_e64 v68, v66, v67, s[16:17]
	ds_bpermute_b32 v72, v195, v190
	ds_bpermute_b32 v68, v195, v68
	v_cndmask_b32_e64 v69, v189, v188, s[16:17]
	v_cndmask_b32_e64 v66, v67, v66, s[16:17]
	s_waitcnt lgkmcnt(1)
	v_add_f32_e32 v69, v69, v72
	s_waitcnt lgkmcnt(0)
	v_add_f32_e32 v68, v66, v68
	s_setprio 0
	v_lshlrev_b64 v[66:67], 12, v[186:187]
	v_lshl_add_u64 v[66:67], v[184:185], 0, v[66:67]
	global_store_dword v[66:67], v69, off
	global_store_dword v[66:67], v68, off offset:256
	s_waitcnt vmcnt(2)
	v_mov_b64_e32 v[66:67], v[74:75]
	v_mov_b64_e32 v[70:71], v[142:143]
	v_mov_b64_e32 v[68:69], v[76:77]
	v_mov_b64_e32 v[72:73], v[144:145]

; DI float dot16(const unsigned (&a)[8], u32x4 b0, u32x4 b1) {
;     float acc;
;     asm volatile("v_dot2_f32_bf16 %0, %1, %9, 0\n\tv_dot2_f32_bf16 %0, %2, %10, %0\n\tv_dot2_f32_bf16 %0, %3, %11, %0\n\tv_dot2_f32_bf16 %0, %4, %12, %0\n\t"
;                  "v_dot2_f32_bf16 %0, %5, %13, %0\n\tv_dot2_f32_bf16 %0, %6, %14, %0\n\tv_dot2_f32_bf16 %0, %7, %15, %0\n\tv_dot2_f32_bf16 %0, %8, %16, %0\n\ts_nop 2"
;                  : "=&v"(acc)
;                  : "v"(a[0]), "v"(a[1]), "v"(a[2]), "v"(a[3]), "v"(a[4]), "v"(a[5]), "v"(a[6]), "v"(a[7]),
;                    "v"(b0.x), "v"(b0.y), "v"(b0.z), "v"(b0.w), "v"(b1.x), "v"(b1.y), "v"(b1.z), "v"(b1.w));
;     return acc;
; }
; DI float dot_fp8_row(u32x4 u, u32x4 xa, u32x4 xb) {
;     unsigned a[8];
; #pragma unroll
;     for (int j = 0; j < 4; ++j) {
;         a[2 * j] = __builtin_bit_cast(unsigned, __builtin_amdgcn_cvt_scalef32_pk_bf16_fp8(u[j], 1.0f, false));
;         a[2 * j + 1] = __builtin_bit_cast(unsigned, __builtin_amdgcn_cvt_scalef32_pk_bf16_fp8(u[j], 1.0f, true));
;     }
;     return dot16(a, xa, xb);
; }
.LBB0_535:
	s_or_b64 exec, exec, s[0:1]
	s_setprio 1
	s_waitcnt vmcnt(15)
	v_cvt_scalef32_pk_bf16_fp8 v213, v79, 1.0
	v_cvt_scalef32_pk_bf16_fp8 v189, v78, 1.0
	v_cvt_scalef32_pk_bf16_fp8 v212, v78, 1.0 op_sel:[1,0,0]
	v_cvt_scalef32_pk_bf16_fp8 v214, v79, 1.0 op_sel:[1,0,0]
	v_cvt_scalef32_pk_bf16_fp8 v215, v80, 1.0
	v_cvt_scalef32_pk_bf16_fp8 v216, v80, 1.0 op_sel:[1,0,0]
	v_cvt_scalef32_pk_bf16_fp8 v217, v81, 1.0
	v_cvt_scalef32_pk_bf16_fp8 v218, v81, 1.0 op_sel:[1,0,0]
	v_dot2_f32_bf16 v219, v189, v74, 0
	v_dot2_f32_bf16 v219, v212, v75, v219
	v_dot2_f32_bf16 v219, v213, v76, v219
	v_dot2_f32_bf16 v219, v214, v77, v219
	v_dot2_f32_bf16 v219, v215, v142, v219
	v_dot2_f32_bf16 v219, v216, v143, v219
	v_dot2_f32_bf16 v219, v217, v144, v219
	v_dot2_f32_bf16 v219, v218, v145, v219
	s_nop 2
	s_waitcnt vmcnt(14)
	v_cvt_scalef32_pk_bf16_fp8 v213, v83, 1.0
	v_cvt_scalef32_pk_bf16_fp8 v189, v82, 1.0
	v_cvt_scalef32_pk_bf16_fp8 v212, v82, 1.0 op_sel:[1,0,0]
	v_cvt_scalef32_pk_bf16_fp8 v214, v83, 1.0 op_sel:[1,0,0]
	v_cvt_scalef32_pk_bf16_fp8 v215, v84, 1.0
	v_cvt_scalef32_pk_bf16_fp8 v216, v84, 1.0 op_sel:[1,0,0]
	v_cvt_scalef32_pk_bf16_fp8 v217, v85, 1.0
	v_cvt_scalef32_pk_bf16_fp8 v218, v85, 1.0 op_sel:[1,0,0]
	v_dot2_f32_bf16 v220, v189, v74, 0
	v_dot2_f32_bf16 v220, v212, v75, v220
	v_dot2_f32_bf16 v220, v213, v76, v220
	v_dot2_f32_bf16 v220, v214, v77, v220
	v_dot2_f32_bf16 v220, v215, v142, v220
	v_dot2_f32_bf16 v220, v216, v143, v220
	v_dot2_f32_bf16 v220, v217, v144, v220
	v_dot2_f32_bf16 v220, v218, v145, v220
	s_nop 2
	s_waitcnt vmcnt(13)
	v_cvt_scalef32_pk_bf16_fp8 v213, v87, 1.0
	v_cvt_scalef32_pk_bf16_fp8 v189, v86, 1.0
	v_cvt_scalef32_pk_bf16_fp8 v212, v86, 1.0 op_sel:[1,0,0]
	v_cvt_scalef32_pk_bf16_fp8 v214, v87, 1.0 op_sel:[1,0,0]
	v_cvt_scalef32_pk_bf16_fp8 v215, v88, 1.0
	v_cvt_scalef32_pk_bf16_fp8 v216, v88, 1.0 op_sel:[1,0,0]
	v_cvt_scalef32_pk_bf16_fp8 v217, v89, 1.0
	v_cvt_scalef32_pk_bf16_fp8 v218, v89, 1.0 op_sel:[1,0,0]
	v_dot2_f32_bf16 v221, v189, v74, 0
	v_dot2_f32_bf16 v221, v212, v75, v221
	v_dot2_f32_bf16 v221, v213, v76, v221
	v_dot2_f32_bf16 v221, v214, v77, v221
	v_dot2_f32_bf16 v221, v215, v142, v221
	v_dot2_f32_bf16 v221, v216, v143, v221
	v_dot2_f32_bf16 v221, v217, v144, v221
	v_dot2_f32_bf16 v221, v218, v145, v221
	s_nop 2
	s_waitcnt vmcnt(12)
	v_cvt_scalef32_pk_bf16_fp8 v213, v91, 1.0
	v_cvt_scalef32_pk_bf16_fp8 v189, v90, 1.0
	v_cvt_scalef32_pk_bf16_fp8 v212, v90, 1.0 op_sel:[1,0,0]
	v_cvt_scalef32_pk_bf16_fp8 v214, v91, 1.0 op_sel:[1,0,0]
	v_cvt_scalef32_pk_bf16_fp8 v215, v92, 1.0
	v_cvt_scalef32_pk_bf16_fp8 v216, v92, 1.0 op_sel:[1,0,0]
	v_cvt_scalef32_pk_bf16_fp8 v217, v93, 1.0
	v_cvt_scalef32_pk_bf16_fp8 v218, v93, 1.0 op_sel:[1,0,0]
	v_dot2_f32_bf16 v222, v189, v74, 0
	v_dot2_f32_bf16 v222, v212, v75, v222
	v_dot2_f32_bf16 v222, v213, v76, v222
	v_dot2_f32_bf16 v222, v214, v77, v222
	v_dot2_f32_bf16 v222, v215, v142, v222
	v_dot2_f32_bf16 v222, v216, v143, v222
	v_dot2_f32_bf16 v222, v217, v144, v222
	v_dot2_f32_bf16 v222, v218, v145, v222
	s_nop 2
	s_waitcnt vmcnt(11)
	v_cvt_scalef32_pk_bf16_fp8 v213, v95, 1.0
	v_cvt_scalef32_pk_bf16_fp8 v189, v94, 1.0
	v_cvt_scalef32_pk_bf16_fp8 v212, v94, 1.0 op_sel:[1,0,0]
	v_cvt_scalef32_pk_bf16_fp8 v214, v95, 1.0 op_sel:[1,0,0]
	v_cvt_scalef32_pk_bf16_fp8 v215, v96, 1.0
	v_cvt_scalef32_pk_bf16_fp8 v216, v96, 1.0 op_sel:[1,0,0]
	v_cvt_scalef32_pk_bf16_fp8 v217, v97, 1.0
	v_cvt_scalef32_pk_bf16_fp8 v218, v97, 1.0 op_sel:[1,0,0]
	v_dot2_f32_bf16 v223, v189, v74, 0
	v_dot2_f32_bf16 v223, v212, v75, v223
	v_dot2_f32_bf16 v223, v213, v76, v223
	v_dot2_f32_bf16 v223, v214, v77, v223
	v_dot2_f32_bf16 v223, v215, v142, v223
	v_dot2_f32_bf16 v223, v216, v143, v223
	v_dot2_f32_bf16 v223, v217, v144, v223
	v_dot2_f32_bf16 v223, v218, v145, v223
	s_nop 2
	s_waitcnt vmcnt(10)
	v_cvt_scalef32_pk_bf16_fp8 v213, v99, 1.0
	v_cvt_scalef32_pk_bf16_fp8 v189, v98, 1.0
	v_cvt_scalef32_pk_bf16_fp8 v212, v98, 1.0 op_sel:[1,0,0]
	v_cvt_scalef32_pk_bf16_fp8 v214, v99, 1.0 op_sel:[1,0,0]
	v_cvt_scalef32_pk_bf16_fp8 v215, v100, 1.0
	v_cvt_scalef32_pk_bf16_fp8 v216, v100, 1.0 op_sel:[1,0,0]
	v_cvt_scalef32_pk_bf16_fp8 v217, v101, 1.0
	v_cvt_scalef32_pk_bf16_fp8 v218, v101, 1.0 op_sel:[1,0,0]
	v_dot2_f32_bf16 v224, v189, v74, 0
	v_dot2_f32_bf16 v224, v212, v75, v224
	v_dot2_f32_bf16 v224, v213, v76, v224
	v_dot2_f32_bf16 v224, v214, v77, v224
	v_dot2_f32_bf16 v224, v215, v142, v224
	v_dot2_f32_bf16 v224, v216, v143, v224
	v_dot2_f32_bf16 v224, v217, v144, v224
	v_dot2_f32_bf16 v224, v218, v145, v224
	s_nop 2
	s_waitcnt vmcnt(9)
	v_cvt_scalef32_pk_bf16_fp8 v213, v103, 1.0
	v_cvt_scalef32_pk_bf16_fp8 v189, v102, 1.0
	v_cvt_scalef32_pk_bf16_fp8 v212, v102, 1.0 op_sel:[1,0,0]
	v_cvt_scalef32_pk_bf16_fp8 v214, v103, 1.0 op_sel:[1,0,0]
	v_cvt_scalef32_pk_bf16_fp8 v215, v104, 1.0
	v_cvt_scalef32_pk_bf16_fp8 v216, v104, 1.0 op_sel:[1,0,0]
	v_cvt_scalef32_pk_bf16_fp8 v217, v105, 1.0
	v_cvt_scalef32_pk_bf16_fp8 v218, v105, 1.0 op_sel:[1,0,0]
	v_dot2_f32_bf16 v225, v189, v74, 0
	v_dot2_f32_bf16 v225, v212, v75, v225
	v_dot2_f32_bf16 v225, v213, v76, v225
	v_dot2_f32_bf16 v225, v214, v77, v225
	v_dot2_f32_bf16 v225, v215, v142, v225
	v_dot2_f32_bf16 v225, v216, v143, v225
	v_dot2_f32_bf16 v225, v217, v144, v225
	v_dot2_f32_bf16 v225, v218, v145, v225
	s_nop 2
	s_waitcnt vmcnt(8)
; DI float dot16(const unsigned (&a)[8], u32x4 b0, u32x4 b1) {
;     float acc;
;     asm volatile("v_dot2_f32_bf16 %0, %1, %9, 0\n\tv_dot2_f32_bf16 %0, %2, %10, %0\n\tv_dot2_f32_bf16 %0, %3, %11, %0\n\tv_dot2_f32_bf16 %0, %4, %12, %0\n\t"
;                  "v_dot2_f32_bf16 %0, %5, %13, %0\n\tv_dot2_f32_bf16 %0, %6, %14, %0\n\tv_dot2_f32_bf16 %0, %7, %15, %0\n\tv_dot2_f32_bf16 %0, %8, %16, %0\n\ts_nop 2"
;                  : "=&v"(acc)
;                  : "v"(a[0]), "v"(a[1]), "v"(a[2]), "v"(a[3]), "v"(a[4]), "v"(a[5]), "v"(a[6]), "v"(a[7]),
;                    "v"(b0.x), "v"(b0.y), "v"(b0.z), "v"(b0.w), "v"(b1.x), "v"(b1.y), "v"(b1.z), "v"(b1.w));
;     return acc;
; }
; DI float dot_fp8_row(u32x4 u, u32x4 xa, u32x4 xb) {
;     unsigned a[8];
; #pragma unroll
;     for (int j = 0; j < 4; ++j) {
;         a[2 * j] = __builtin_bit_cast(unsigned, __builtin_amdgcn_cvt_scalef32_pk_bf16_fp8(u[j], 1.0f, false));
;         a[2 * j + 1] = __builtin_bit_cast(unsigned, __builtin_amdgcn_cvt_scalef32_pk_bf16_fp8(u[j], 1.0f, true));
;     }
;     return dot16(a, xa, xb);
; }
	v_cvt_scalef32_pk_bf16_fp8 v213, v107, 1.0
	v_cvt_scalef32_pk_bf16_fp8 v189, v106, 1.0
	v_cvt_scalef32_pk_bf16_fp8 v212, v106, 1.0 op_sel:[1,0,0]
	v_cvt_scalef32_pk_bf16_fp8 v214, v107, 1.0 op_sel:[1,0,0]
	v_cvt_scalef32_pk_bf16_fp8 v215, v108, 1.0
	v_cvt_scalef32_pk_bf16_fp8 v216, v108, 1.0 op_sel:[1,0,0]
	v_cvt_scalef32_pk_bf16_fp8 v218, v109, 1.0
	v_cvt_scalef32_pk_bf16_fp8 v226, v109, 1.0 op_sel:[1,0,0]
	v_dot2_f32_bf16 v227, v189, v74, 0
	v_dot2_f32_bf16 v227, v212, v75, v227
	v_dot2_f32_bf16 v227, v213, v76, v227
	v_dot2_f32_bf16 v227, v214, v77, v227
	v_dot2_f32_bf16 v227, v215, v142, v227
	v_dot2_f32_bf16 v227, v216, v143, v227
	v_dot2_f32_bf16 v227, v218, v144, v227
	v_dot2_f32_bf16 v227, v226, v145, v227
	s_nop 2
	v_cndmask_b32_e64 v213, v220, v224, s[12:13]
	ds_bpermute_b32 v213, v193, v213
	v_cndmask_b32_e64 v214, v221, v225, s[12:13]
	ds_bpermute_b32 v214, v193, v214
	v_cndmask_b32_e64 v215, v222, v227, s[12:13]
	v_cndmask_b32_e64 v217, v219, v223, s[12:13]
	ds_bpermute_b32 v215, v193, v215
	ds_bpermute_b32 v217, v193, v217
	v_cndmask_b32_e64 v212, v224, v220, s[12:13]
	s_waitcnt lgkmcnt(3)
	v_add_f32_e32 v212, v212, v213
	v_cndmask_b32_e64 v213, v225, v221, s[12:13]
	s_waitcnt lgkmcnt(2)
	v_add_f32_e32 v213, v213, v214
	v_cndmask_b32_e64 v214, v227, v222, s[12:13]
	v_cndmask_b32_e64 v189, v223, v219, s[12:13]
	s_waitcnt lgkmcnt(1)
	v_add_f32_e32 v214, v214, v215
	s_waitcnt lgkmcnt(0)
	v_add_f32_e32 v189, v189, v217
	v_cndmask_b32_e64 v216, v212, v214, s[14:15]
	v_cndmask_b32_e64 v215, v189, v213, s[14:15]
	ds_bpermute_b32 v216, v194, v216
	ds_bpermute_b32 v215, v194, v215
	v_cndmask_b32_e64 v212, v214, v212, s[14:15]
	v_cndmask_b32_e64 v189, v213, v189, s[14:15]
	s_waitcnt vmcnt(7)
	v_cvt_scalef32_pk_bf16_fp8 v214, v110, 1.0
	s_waitcnt lgkmcnt(1)
	v_add_f32_e32 v212, v212, v216
	v_cvt_scalef32_pk_bf16_fp8 v216, v111, 1.0
	s_waitcnt lgkmcnt(0)
	v_add_f32_e32 v189, v189, v215
	v_cvt_scalef32_pk_bf16_fp8 v215, v110, 1.0 op_sel:[1,0,0]
	v_cvt_scalef32_pk_bf16_fp8 v217, v111, 1.0 op_sel:[1,0,0]
	v_cvt_scalef32_pk_bf16_fp8 v218, v112, 1.0
	v_cvt_scalef32_pk_bf16_fp8 v219, v112, 1.0 op_sel:[1,0,0]
	v_cvt_scalef32_pk_bf16_fp8 v220, v113, 1.0
	v_cvt_scalef32_pk_bf16_fp8 v221, v113, 1.0 op_sel:[1,0,0]
	v_dot2_f32_bf16 v222, v214, v74, 0
	v_dot2_f32_bf16 v222, v215, v75, v222
	v_dot2_f32_bf16 v222, v216, v76, v222
	v_dot2_f32_bf16 v222, v217, v77, v222
	v_dot2_f32_bf16 v222, v218, v142, v222
	v_dot2_f32_bf16 v222, v219, v143, v222
	v_dot2_f32_bf16 v222, v220, v144, v222
	v_dot2_f32_bf16 v222, v221, v145, v222
	s_nop 2
	s_waitcnt vmcnt(6)
	v_cvt_scalef32_pk_bf16_fp8 v216, v115, 1.0
	v_cvt_scalef32_pk_bf16_fp8 v214, v114, 1.0
	v_cvt_scalef32_pk_bf16_fp8 v215, v114, 1.0 op_sel:[1,0,0]
	v_cvt_scalef32_pk_bf16_fp8 v217, v115, 1.0 op_sel:[1,0,0]
	v_cvt_scalef32_pk_bf16_fp8 v218, v116, 1.0
	v_cvt_scalef32_pk_bf16_fp8 v219, v116, 1.0 op_sel:[1,0,0]
	v_cvt_scalef32_pk_bf16_fp8 v220, v117, 1.0
	v_cvt_scalef32_pk_bf16_fp8 v221, v117, 1.0 op_sel:[1,0,0]
	v_dot2_f32_bf16 v223, v214, v74, 0
	v_dot2_f32_bf16 v223, v215, v75, v223
	v_dot2_f32_bf16 v223, v216, v76, v223
	v_dot2_f32_bf16 v223, v217, v77, v223
	v_dot2_f32_bf16 v223, v218, v142, v223
	v_dot2_f32_bf16 v223, v219, v143, v223
	v_dot2_f32_bf16 v223, v220, v144, v223
	v_dot2_f32_bf16 v223, v221, v145, v223
	s_nop 2
	s_waitcnt vmcnt(5)
	v_cvt_scalef32_pk_bf16_fp8 v216, v119, 1.0
	v_cvt_scalef32_pk_bf16_fp8 v214, v118, 1.0
	v_cvt_scalef32_pk_bf16_fp8 v215, v118, 1.0 op_sel:[1,0,0]
	v_cvt_scalef32_pk_bf16_fp8 v217, v119, 1.0 op_sel:[1,0,0]
	v_cvt_scalef32_pk_bf16_fp8 v218, v120, 1.0
	v_cvt_scalef32_pk_bf16_fp8 v219, v120, 1.0 op_sel:[1,0,0]
	v_cvt_scalef32_pk_bf16_fp8 v220, v121, 1.0
	v_cvt_scalef32_pk_bf16_fp8 v221, v121, 1.0 op_sel:[1,0,0]
	v_dot2_f32_bf16 v224, v214, v74, 0
	v_dot2_f32_bf16 v224, v215, v75, v224
	v_dot2_f32_bf16 v224, v216, v76, v224
	v_dot2_f32_bf16 v224, v217, v77, v224
	v_dot2_f32_bf16 v224, v218, v142, v224
	v_dot2_f32_bf16 v224, v219, v143, v224
	v_dot2_f32_bf16 v224, v220, v144, v224
	v_dot2_f32_bf16 v224, v221, v145, v224
	s_nop 2
	s_waitcnt vmcnt(4)
	v_cvt_scalef32_pk_bf16_fp8 v216, v123, 1.0
	v_cvt_scalef32_pk_bf16_fp8 v214, v122, 1.0
	v_cvt_scalef32_pk_bf16_fp8 v215, v122, 1.0 op_sel:[1,0,0]
	v_cvt_scalef32_pk_bf16_fp8 v217, v123, 1.0 op_sel:[1,0,0]
	v_cvt_scalef32_pk_bf16_fp8 v218, v124, 1.0
	v_cvt_scalef32_pk_bf16_fp8 v219, v124, 1.0 op_sel:[1,0,0]
	v_cvt_scalef32_pk_bf16_fp8 v220, v125, 1.0
	v_cvt_scalef32_pk_bf16_fp8 v221, v125, 1.0 op_sel:[1,0,0]
	v_dot2_f32_bf16 v225, v214, v74, 0
	v_dot2_f32_bf16 v225, v215, v75, v225
	v_dot2_f32_bf16 v225, v216, v76, v225
	v_dot2_f32_bf16 v225, v217, v77, v225
	v_dot2_f32_bf16 v225, v218, v142, v225
	v_dot2_f32_bf16 v225, v219, v143, v225
	v_dot2_f32_bf16 v225, v220, v144, v225
	v_dot2_f32_bf16 v225, v221, v145, v225
	s_nop 2
	s_waitcnt vmcnt(3)
	v_cvt_scalef32_pk_bf16_fp8 v216, v127, 1.0
	v_cvt_scalef32_pk_bf16_fp8 v214, v126, 1.0
	v_cvt_scalef32_pk_bf16_fp8 v215, v126, 1.0 op_sel:[1,0,0]
	v_cvt_scalef32_pk_bf16_fp8 v217, v127, 1.0 op_sel:[1,0,0]
	v_cvt_scalef32_pk_bf16_fp8 v218, v128, 1.0
	v_cvt_scalef32_pk_bf16_fp8 v219, v128, 1.0 op_sel:[1,0,0]
	v_cvt_scalef32_pk_bf16_fp8 v220, v129, 1.0
	v_cvt_scalef32_pk_bf16_fp8 v221, v129, 1.0 op_sel:[1,0,0]
	v_dot2_f32_bf16 v226, v214, v74, 0
	v_dot2_f32_bf16 v226, v215, v75, v226
	v_dot2_f32_bf16 v226, v216, v76, v226
	v_dot2_f32_bf16 v226, v217, v77, v226
	v_dot2_f32_bf16 v226, v218, v142, v226
	v_dot2_f32_bf16 v226, v219, v143, v226
	v_dot2_f32_bf16 v226, v220, v144, v226
	v_dot2_f32_bf16 v226, v221, v145, v226
	s_nop 2
	s_waitcnt vmcnt(2)
; #define U_ISSUE(SEG, E0, E1) { _Pragma("unroll") for (int b = 0; b < 16; ++b) { const int e = __shfl((b < 8) ? (E0) : (E1), (b & 7) * 8 + grp); SEG[b] = *(const u32x4*)(ub + (size_t)e * DM); } }
; DI void peer_u_phase(const bf16_t* __restrict__ x1, const int* __restrict__ eidx, const unsigned char* __restrict__ U8, float* __restrict__ ph) {
;     ...
;             if (n1) {
;                 xa = xan; xb = xbn;
;                 if (n2) { U_ISSUE(sa, e0nn, e1nn) xan = *(const u32x4*)(xb_ + (size_t)(t + 2 * step) * DM); xbn = *(const u32x4*)(xb_ + (size_t)(t + 2 * step) * DM + 8); }
	v_cvt_scalef32_pk_bf16_fp8 v216, v131, 1.0
	v_cvt_scalef32_pk_bf16_fp8 v214, v130, 1.0
	v_cvt_scalef32_pk_bf16_fp8 v215, v130, 1.0 op_sel:[1,0,0]
	v_cvt_scalef32_pk_bf16_fp8 v217, v131, 1.0 op_sel:[1,0,0]
	v_cvt_scalef32_pk_bf16_fp8 v218, v132, 1.0
	v_cvt_scalef32_pk_bf16_fp8 v219, v132, 1.0 op_sel:[1,0,0]
	v_cvt_scalef32_pk_bf16_fp8 v220, v133, 1.0
	v_cvt_scalef32_pk_bf16_fp8 v221, v133, 1.0 op_sel:[1,0,0]
	v_dot2_f32_bf16 v227, v214, v74, 0
	v_dot2_f32_bf16 v227, v215, v75, v227
	v_dot2_f32_bf16 v227, v216, v76, v227
	v_dot2_f32_bf16 v227, v217, v77, v227
	v_dot2_f32_bf16 v227, v218, v142, v227
	v_dot2_f32_bf16 v227, v219, v143, v227
	v_dot2_f32_bf16 v227, v220, v144, v227
	v_dot2_f32_bf16 v227, v221, v145, v227
	s_nop 2
	s_waitcnt vmcnt(1)
	v_cvt_scalef32_pk_bf16_fp8 v216, v135, 1.0
	v_cvt_scalef32_pk_bf16_fp8 v214, v134, 1.0
	v_cvt_scalef32_pk_bf16_fp8 v215, v134, 1.0 op_sel:[1,0,0]
	v_cvt_scalef32_pk_bf16_fp8 v217, v135, 1.0 op_sel:[1,0,0]
	v_cvt_scalef32_pk_bf16_fp8 v218, v136, 1.0
	v_cvt_scalef32_pk_bf16_fp8 v219, v136, 1.0 op_sel:[1,0,0]
	v_cvt_scalef32_pk_bf16_fp8 v220, v137, 1.0
	v_cvt_scalef32_pk_bf16_fp8 v221, v137, 1.0 op_sel:[1,0,0]
	v_dot2_f32_bf16 v228, v214, v74, 0
	v_dot2_f32_bf16 v228, v215, v75, v228
	v_dot2_f32_bf16 v228, v216, v76, v228
	v_dot2_f32_bf16 v228, v217, v77, v228
	v_dot2_f32_bf16 v228, v218, v142, v228
	v_dot2_f32_bf16 v228, v219, v143, v228
	v_dot2_f32_bf16 v228, v220, v144, v228
	v_dot2_f32_bf16 v228, v221, v145, v228
	s_nop 2
	s_waitcnt vmcnt(0)
	v_cvt_scalef32_pk_bf16_fp8 v216, v139, 1.0
	v_cvt_scalef32_pk_bf16_fp8 v214, v138, 1.0
	v_cvt_scalef32_pk_bf16_fp8 v215, v138, 1.0 op_sel:[1,0,0]
	v_cvt_scalef32_pk_bf16_fp8 v217, v139, 1.0 op_sel:[1,0,0]
	v_cvt_scalef32_pk_bf16_fp8 v218, v140, 1.0
	v_cvt_scalef32_pk_bf16_fp8 v219, v140, 1.0 op_sel:[1,0,0]
	v_cvt_scalef32_pk_bf16_fp8 v221, v141, 1.0
	v_cvt_scalef32_pk_bf16_fp8 v229, v141, 1.0 op_sel:[1,0,0]
	v_dot2_f32_bf16 v230, v214, v74, 0
	v_dot2_f32_bf16 v230, v215, v75, v230
	v_dot2_f32_bf16 v230, v216, v76, v230
	v_dot2_f32_bf16 v230, v217, v77, v230
	v_dot2_f32_bf16 v230, v218, v142, v230
	v_dot2_f32_bf16 v230, v219, v143, v230
	v_dot2_f32_bf16 v230, v221, v144, v230
	v_dot2_f32_bf16 v230, v229, v145, v230
	s_nop 2
	v_cndmask_b32_e64 v216, v223, v227, s[12:13]
	ds_bpermute_b32 v216, v193, v216
	v_cndmask_b32_e64 v217, v224, v228, s[12:13]
	v_cndmask_b32_e64 v220, v222, v226, s[12:13]
	ds_bpermute_b32 v217, v193, v217
	v_cndmask_b32_e64 v218, v225, v230, s[12:13]
	ds_bpermute_b32 v220, v193, v220
	ds_bpermute_b32 v218, v193, v218
	v_cndmask_b32_e64 v215, v227, v223, s[12:13]
	s_waitcnt lgkmcnt(3)
	v_add_f32_e32 v215, v215, v216
	v_cndmask_b32_e64 v216, v228, v224, s[12:13]
	v_cndmask_b32_e64 v214, v226, v222, s[12:13]
	s_waitcnt lgkmcnt(2)
	v_add_f32_e32 v216, v216, v217
	v_cndmask_b32_e64 v217, v230, v225, s[12:13]
	s_waitcnt lgkmcnt(1)
	v_add_f32_e32 v214, v214, v220
	s_waitcnt lgkmcnt(0)
	v_add_f32_e32 v217, v217, v218
	v_cndmask_b32_e64 v218, v214, v216, s[14:15]
	v_cndmask_b32_e64 v219, v215, v217, s[14:15]
	ds_bpermute_b32 v218, v194, v218
	ds_bpermute_b32 v219, v194, v219
	v_cndmask_b32_e64 v214, v216, v214, s[14:15]
	v_cndmask_b32_e64 v215, v217, v215, s[14:15]
	v_cndmask_b32_e64 v213, v189, v212, s[16:17]
	s_waitcnt lgkmcnt(1)
	v_add_f32_e32 v214, v214, v218
	s_waitcnt lgkmcnt(0)
	v_add_f32_e32 v215, v215, v219
	ds_bpermute_b32 v213, v195, v213
	v_cndmask_b32_e64 v216, v214, v215, s[16:17]
	ds_bpermute_b32 v216, v195, v216
	v_cndmask_b32_e64 v189, v212, v189, s[16:17]
	s_waitcnt lgkmcnt(1)
	v_add_f32_e32 v217, v189, v213
	v_cndmask_b32_e64 v189, v215, v214, s[16:17]
	s_waitcnt lgkmcnt(0)
	v_add_f32_e32 v214, v189, v216
	s_setprio 0
	v_ashrrev_i32_e32 v189, 31, v188
	v_lshlrev_b64 v[212:213], 12, v[188:189]
	v_lshl_add_u64 v[212:213], v[184:185], 0, v[212:213]
	global_store_dword v[212:213], v217, off
	global_store_dword v[212:213], v214, off offset:256
	s_and_saveexec_b64 s[74:75], s[18:19]
	s_cbranch_execz .LBB0_530
	v_mov_b64_e32 v[144:145], v[72:73]
	v_mov_b64_e32 v[76:77], v[68:69]
	v_mov_b64_e32 v[142:143], v[70:71]
	v_mov_b64_e32 v[74:75], v[66:67]
	s_and_saveexec_b64 s[0:1], s[20:21]
	s_cbranch_execz .LBB0_538
	ds_bpermute_b32 v74, v1, v211
	ds_bpermute_b32 v76, v149, v211
	ds_bpermute_b32 v86, v153, v211
	ds_bpermute_b32 v88, v198, v211
	ds_bpermute_b32 v94, v199, v211
	s_waitcnt lgkmcnt(4)
	ds_bpermute_b32 v96, v200, v211
	s_waitcnt lgkmcnt(4)
	v_lshl_add_u32 v74, v74, 7, v252
	ds_bpermute_b32 v102, v201, v211
	v_lshl_add_u32 v76, v76, 7, v252
	s_waitcnt lgkmcnt(4)
	ds_bpermute_b32 v104, v202, v211
	global_load_dwordx4 v[78:81], v74, s[98:99]
	global_load_dwordx4 v[82:85], v76, s[98:99]
	v_lshl_add_u32 v74, v86, 7, v252
	s_waitcnt lgkmcnt(4)
	ds_bpermute_b32 v110, v1, v191
	v_lshl_add_u32 v76, v88, 7, v252
	s_waitcnt lgkmcnt(4)
	ds_bpermute_b32 v112, v149, v191
	global_load_dwordx4 v[86:89], v74, s[98:99]
	global_load_dwordx4 v[90:93], v76, s[98:99]
	v_lshl_add_u32 v74, v94, 7, v252
	s_waitcnt lgkmcnt(4)
	ds_bpermute_b32 v118, v153, v191
	v_lshl_add_u32 v76, v96, 7, v252
	s_waitcnt lgkmcnt(4)
	ds_bpermute_b32 v120, v198, v191
	global_load_dwordx4 v[94:97], v74, s[98:99]
	global_load_dwordx4 v[98:101], v76, s[98:99]
	v_lshl_add_u32 v74, v102, 7, v252
	s_waitcnt lgkmcnt(4)
	ds_bpermute_b32 v126, v199, v191
	v_lshl_add_u32 v76, v104, 7, v252
	s_waitcnt lgkmcnt(4)
	ds_bpermute_b32 v128, v200, v191
	global_load_dwordx4 v[102:105], v74, s[98:99]
	global_load_dwordx4 v[106:109], v76, s[98:99]
	v_lshl_add_u32 v74, v110, 7, v252
	s_waitcnt lgkmcnt(4)
	ds_bpermute_b32 v134, v201, v191
	v_lshl_add_u32 v76, v112, 7, v252
	s_waitcnt lgkmcnt(4)
	ds_bpermute_b32 v136, v202, v191
	global_load_dwordx4 v[110:113], v74, s[98:99]
	global_load_dwordx4 v[114:117], v76, s[98:99]
	v_lshl_add_u32 v74, v118, 7, v252
	s_waitcnt lgkmcnt(4)
	v_lshl_add_u32 v76, v120, 7, v252
	s_waitcnt lgkmcnt(3)
	global_load_dwordx4 v[118:121], v74, s[98:99]
	global_load_dwordx4 v[122:125], v76, s[98:99]
	v_lshl_add_u32 v74, v126, 7, v252
	s_waitcnt lgkmcnt(2)
	v_lshl_add_u32 v76, v128, 7, v252
	s_waitcnt lgkmcnt(1)
	global_load_dwordx4 v[126:129], v74, s[98:99]
	global_load_dwordx4 v[130:133], v76, s[98:99]
	v_lshl_add_u32 v74, v134, 7, v252
	s_waitcnt lgkmcnt(0)
	v_lshl_add_u32 v76, v136, 7, v252
	v_ashrrev_i32_e32 v191, 31, v190
	global_load_dwordx4 v[134:137], v74, s[98:99]
	global_load_dwordx4 v[138:141], v76, s[98:99]
	v_lshlrev_b64 v[74:75], 11, v[190:191]
	v_lshl_add_u64 v[74:75], v[182:183], 0, v[74:75]
	global_load_dwordx4 v[142:145], v[74:75], off offset:16
	s_nop 0
	global_load_dwordx4 v[74:77], v[74:75], off

; DI float gelu_exact(float v) { return 0.5f * v * (1.0f + erff(v * 0.70710678118654752f)); }
; DI void peer_hw_phase(const float* __restrict__ ph, const int* __restrict__ eidx, const float* __restrict__ su, const float* __restrict__ sv, float* __restrict__ gws) {
;     const size_t n = (size_t)T_TOK * 128, nthreads = (size_t)gridDim.x * blockDim.x;
;     for (size_t i = (size_t)blockIdx.x * blockDim.x + threadIdx.x; i < n; i += nthreads) {
;         float hsum = 0.f;
; #pragma unroll
;         for (int j = 0; j < 8; ++j) hsum += ph[(size_t)j * n + i];
;         const int e = eidx[i];
;         gws[i] = gws[i] * gelu_exact(hsum * su[e]) * sv[e];
;     }
; }
.LBB0_592:
	s_or_b64 exec, exec, s[0:1]
	v_lshl_add_u64 v[144:145], v[176:177], 2, s[90:91]
	s_waitcnt lgkmcnt(0)
	s_barrier
	s_mov_b64 s[0:1], exec
	v_readlane_b32 s10, v253, 3
	v_readlane_b32 s11, v253, 4
	s_and_b64 s[10:11], s[0:1], s[10:11]
	s_mov_b64 exec, s[10:11]
	s_cbranch_execz .LBB0_599
	s_add_u32 s10, s90, 0x3d400000
	s_addc_u32 s11, s91, 0
	s_add_u32 s12, s90, 0x3d420000
	s_addc_u32 s13, s91, 0
	v_lshl_add_u64 v[2:3], v[176:177], 2, s[90:91]
	v_lshrrev_b32_e32 v22, 7, v176
	v_lshlrev_b32_e32 v22, 12, v22
	v_and_b32_e32 v23, 0x7f, v176
	v_lshl_or_b32 v22, v23, 2, v22
	v_mov_b32_e32 v23, 0
	v_lshl_add_u64 v[22:23], v[22:23], 0, s[90:91]
	s_lshl_b64 s[96:97], s[34:35], 5
	s_lshl_b64 s[14:15], s[34:35], 2
	s_mov_b64 s[16:17], 0
	s_mov_b64 s[18:19], 0x32000000
	s_mov_b32 s27, 0x378e98ab
	s_mov_b32 s42, 0x3b7cd369
	s_mov_b32 s43, 0xbcc618b2
	s_mov_b32 s56, 0x3dda74e4
	s_mov_b32 s57, 0x3f228afd
	s_mov_b32 s58, 0x3e03c728
	s_mov_b32 s59, 0xbfb8aa3b
	s_mov_b32 s70, 0x42ce8ed0
	s_mov_b32 s71, 0xc2b17218
	v_mov_b32_e32 v1, 0x3ba10414
	s_brev_b32 s72, -2
	s_mov_b64 s[20:21], 0x7fffff
	v_mov_b32_e32 v8, 0xb9c68948
	v_mov_b32_e32 v9, 0x7f800000
	v_mov_b64_e32 v[4:5], v[176:177]
	s_branch .LBB0_595
.LBB0_594:
	s_or_b64 exec, exec, s[24:25]
	v_lshl_add_u64 v[22:23], v[22:23], 0, s[96:97]
	v_lshl_add_u64 v[6:7], v[6:7], 2, s[12:13]
	global_load_dword v14, v[6:7], off
	v_bfi_b32 v12, s72, v13, v12
	v_mul_f32_e32 v11, 0.5, v11
	v_add_f32_e32 v12, 1.0, v12
	v_lshl_add_u64 v[4:5], v[4:5], 0, s[34:35]
	v_mul_f32_e32 v11, v11, v12
	v_cmp_lt_u64_e32 vcc, s[20:21], v[4:5]
	s_waitcnt vmcnt(1)
	v_mul_f32_e32 v10, v10, v11
	v_lshl_add_u64 v[6:7], v[2:3], 0, s[18:19]
	s_or_b64 s[16:17], vcc, s[16:17]
	v_lshl_add_u64 v[2:3], v[2:3], 0, s[14:15]
	s_waitcnt vmcnt(0)
	v_mul_f32_e32 v10, v14, v10
	global_store_dword v[6:7], v10, off
	s_andn2_b64 exec, exec, s[16:17]
	s_cbranch_execz .LBB0_599
.LBB0_595:
	v_add_co_u32_e32 v6, vcc, 0x30000000, v2
	s_nop 1
	v_addc_co_u32_e32 v7, vcc, 0, v3, vcc
	global_load_dword v6, v[6:7], off
	s_nop 0
	global_load_dword v24, v[22:23], off
	global_load_dword v25, v[22:23], off offset:512
	global_load_dword v26, v[22:23], off offset:1024
	global_load_dword v14, v[22:23], off offset:1536
	global_load_dword v15, v[22:23], off offset:2048
	global_load_dword v16, v[22:23], off offset:2560
	global_load_dword v17, v[22:23], off offset:3072
	global_load_dword v18, v[22:23], off offset:3584
	v_add_co_u32_e32 v10, vcc, 0x32000000, v2
	s_waitcnt vmcnt(8)
	v_ashrrev_i32_e32 v7, 31, v6
	v_lshl_add_u64 v[12:13], v[6:7], 2, s[10:11]
	global_load_dword v12, v[12:13], off
	v_addc_co_u32_e32 v11, vcc, 0, v3, vcc
	global_load_dword v10, v[10:11], off
	s_waitcnt vmcnt(9)
	v_add_f32_e32 v11, 0, v24
	s_waitcnt vmcnt(8)
	v_add_f32_e32 v11, v11, v25
	s_waitcnt vmcnt(7)
	v_add_f32_e32 v11, v11, v26
	s_waitcnt vmcnt(6)
	v_add_f32_e32 v11, v11, v14
	s_waitcnt vmcnt(5)
	v_add_f32_e32 v11, v11, v15
	s_waitcnt vmcnt(4)
	v_add_f32_e32 v11, v11, v16
	s_waitcnt vmcnt(3)
	v_add_f32_e32 v11, v11, v17
	s_waitcnt vmcnt(2)
	v_add_f32_e32 v11, v11, v18
	s_waitcnt vmcnt(1)
	v_mul_f32_e32 v11, v11, v12
	v_mul_f32_e32 v12, 0x3f3504f3, v11
	v_cmp_nlt_f32_e64 s[24:25], |v12|, 1.0
	s_and_saveexec_b64 s[46:47], s[24:25]
	s_xor_b64 s[24:25], exec, s[46:47]
	s_cbranch_execz .LBB0_597
	v_fma_f32 v13, |v12|, s27, v8
	v_fma_f32 v13, |v12|, v13, s42
	v_fma_f32 v13, |v12|, v13, s43
	v_fma_f32 v13, |v12|, v13, s56
	v_fma_f32 v13, |v12|, v13, s57
	v_fma_f32 v13, |v12|, v13, s58
	v_fma_f32 v13, |v12|, v13, |v12|
	v_mul_f32_e32 v14, 0xbfb8aa3b, v13
	v_fma_f32 v15, v13, s59, -v14
	v_rndne_f32_e32 v16, v14
	v_fmac_f32_e32 v15, 0xb2a5705f, v13
	v_sub_f32_e32 v14, v14, v16
	v_add_f32_e32 v14, v14, v15
	v_cvt_i32_f32_e32 v15, v16
	v_exp_f32_e32 v14, v14
	v_cmp_nlt_f32_e32 vcc, s70, v13
	v_ldexp_f32 v14, v14, v15
	s_nop 0
	v_cndmask_b32_e32 v14, 0, v14, vcc
	v_cmp_ngt_f32_e32 vcc, s71, v13
	s_nop 1
	v_cndmask_b32_e32 v13, v9, v14, vcc
	v_sub_f32_e32 v13, 1.0, v13

; DI float dot16(const unsigned (&a)[8], u32x4 b0, u32x4 b1) {
;     float acc;
;     asm volatile("v_dot2_f32_bf16 %0, %1, %9, 0\n\tv_dot2_f32_bf16 %0, %2, %10, %0\n\tv_dot2_f32_bf16 %0, %3, %11, %0\n\tv_dot2_f32_bf16 %0, %4, %12, %0\n\t"
;                  "v_dot2_f32_bf16 %0, %5, %13, %0\n\tv_dot2_f32_bf16 %0, %6, %14, %0\n\tv_dot2_f32_bf16 %0, %7, %15, %0\n\tv_dot2_f32_bf16 %0, %8, %16, %0\n\ts_nop 2"
;                  : "=&v"(acc)
;                  : "v"(a[0]), "v"(a[1]), "v"(a[2]), "v"(a[3]), "v"(a[4]), "v"(a[5]), "v"(a[6]), "v"(a[7]),
;                    "v"(b0.x), "v"(b0.y), "v"(b0.z), "v"(b0.w), "v"(b1.x), "v"(b1.y), "v"(b1.z), "v"(b1.w));
;     return acc;
; }
; DI float dot_fp8_row(u32x4 u, u32x4 xa, u32x4 xb) {
;     unsigned a[8];
; #pragma unroll
;     for (int j = 0; j < 4; ++j) {
;         a[2 * j] = __builtin_bit_cast(unsigned, __builtin_amdgcn_cvt_scalef32_pk_bf16_fp8(u[j], 1.0f, false));
;         a[2 * j + 1] = __builtin_bit_cast(unsigned, __builtin_amdgcn_cvt_scalef32_pk_bf16_fp8(u[j], 1.0f, true));
;     }
;     return dot16(a, xa, xb);
; }
.LBB0_1226:
	s_or_b64 exec, exec, s[0:1]
	s_lshl_b32 s2, s24, 9
	v_lshl_add_u64 v[178:179], v[164:165], 0, s[2:3]
	s_mov_b64 s[20:21], 0
	v_mov_b32_e32 v182, v150
	s_branch .LBB0_1229
.LBB0_1227:
	s_or_b64 exec, exec, s[14:15]
	s_setprio 1
	v_cvt_scalef32_pk_bf16_fp8 v184, v5, 1.0
	v_cvt_scalef32_pk_bf16_fp8 v182, v4, 1.0
	v_cvt_scalef32_pk_bf16_fp8 v183, v4, 1.0 op_sel:[1,0,0]
	v_cvt_scalef32_pk_bf16_fp8 v185, v5, 1.0 op_sel:[1,0,0]
	v_cvt_scalef32_pk_bf16_fp8 v201, v6, 1.0
	v_cvt_scalef32_pk_bf16_fp8 v202, v6, 1.0 op_sel:[1,0,0]
	v_cvt_scalef32_pk_bf16_fp8 v203, v7, 1.0
	v_cvt_scalef32_pk_bf16_fp8 v204, v7, 1.0 op_sel:[1,0,0]
	v_dot2_f32_bf16 v205, v182, v64, 0
	v_dot2_f32_bf16 v205, v183, v65, v205
	v_dot2_f32_bf16 v205, v184, v66, v205
	v_dot2_f32_bf16 v205, v185, v67, v205
	v_dot2_f32_bf16 v205, v201, v68, v205
	v_dot2_f32_bf16 v205, v202, v69, v205
	v_dot2_f32_bf16 v205, v203, v70, v205
	v_dot2_f32_bf16 v205, v204, v71, v205
	s_nop 2
	v_cvt_scalef32_pk_bf16_fp8 v184, v1, 1.0
	v_cvt_scalef32_pk_bf16_fp8 v182, v0, 1.0
	v_cvt_scalef32_pk_bf16_fp8 v183, v0, 1.0 op_sel:[1,0,0]
	v_cvt_scalef32_pk_bf16_fp8 v185, v1, 1.0 op_sel:[1,0,0]
	v_cvt_scalef32_pk_bf16_fp8 v201, v2, 1.0
	v_cvt_scalef32_pk_bf16_fp8 v202, v2, 1.0 op_sel:[1,0,0]
	v_cvt_scalef32_pk_bf16_fp8 v203, v3, 1.0
	v_cvt_scalef32_pk_bf16_fp8 v204, v3, 1.0 op_sel:[1,0,0]
	v_dot2_f32_bf16 v206, v182, v64, 0
	v_dot2_f32_bf16 v206, v183, v65, v206
	v_dot2_f32_bf16 v206, v184, v66, v206
	v_dot2_f32_bf16 v206, v185, v67, v206
	v_dot2_f32_bf16 v206, v201, v68, v206
	v_dot2_f32_bf16 v206, v202, v69, v206
	v_dot2_f32_bf16 v206, v203, v70, v206
	v_dot2_f32_bf16 v206, v204, v71, v206
	s_nop 2
	v_cvt_scalef32_pk_bf16_fp8 v184, v13, 1.0
	v_cvt_scalef32_pk_bf16_fp8 v182, v12, 1.0
	v_cvt_scalef32_pk_bf16_fp8 v183, v12, 1.0 op_sel:[1,0,0]
	v_cvt_scalef32_pk_bf16_fp8 v185, v13, 1.0 op_sel:[1,0,0]
	v_cvt_scalef32_pk_bf16_fp8 v201, v14, 1.0
	v_cvt_scalef32_pk_bf16_fp8 v202, v14, 1.0 op_sel:[1,0,0]
	v_cvt_scalef32_pk_bf16_fp8 v203, v15, 1.0
	v_cvt_scalef32_pk_bf16_fp8 v204, v15, 1.0 op_sel:[1,0,0]
	v_dot2_f32_bf16 v207, v182, v64, 0
	v_dot2_f32_bf16 v207, v183, v65, v207
	v_dot2_f32_bf16 v207, v184, v66, v207
	v_dot2_f32_bf16 v207, v185, v67, v207
	v_dot2_f32_bf16 v207, v201, v68, v207
	v_dot2_f32_bf16 v207, v202, v69, v207
	v_dot2_f32_bf16 v207, v203, v70, v207
	v_dot2_f32_bf16 v207, v204, v71, v207
	s_nop 2
	v_cvt_scalef32_pk_bf16_fp8 v184, v9, 1.0
	v_cvt_scalef32_pk_bf16_fp8 v182, v8, 1.0
	v_cvt_scalef32_pk_bf16_fp8 v183, v8, 1.0 op_sel:[1,0,0]
	v_cvt_scalef32_pk_bf16_fp8 v185, v9, 1.0 op_sel:[1,0,0]
	v_cvt_scalef32_pk_bf16_fp8 v201, v10, 1.0
	v_cvt_scalef32_pk_bf16_fp8 v202, v10, 1.0 op_sel:[1,0,0]
	v_cvt_scalef32_pk_bf16_fp8 v203, v11, 1.0
	v_cvt_scalef32_pk_bf16_fp8 v204, v11, 1.0 op_sel:[1,0,0]
	v_dot2_f32_bf16 v208, v182, v64, 0
	v_dot2_f32_bf16 v208, v183, v65, v208
	v_dot2_f32_bf16 v208, v184, v66, v208
	v_dot2_f32_bf16 v208, v185, v67, v208
	v_dot2_f32_bf16 v208, v201, v68, v208
	v_dot2_f32_bf16 v208, v202, v69, v208
	v_dot2_f32_bf16 v208, v203, v70, v208
	v_dot2_f32_bf16 v208, v204, v71, v208
	s_nop 2
	v_cvt_scalef32_pk_bf16_fp8 v184, v21, 1.0
	v_cvt_scalef32_pk_bf16_fp8 v182, v20, 1.0
	v_cvt_scalef32_pk_bf16_fp8 v183, v20, 1.0 op_sel:[1,0,0]
	v_cvt_scalef32_pk_bf16_fp8 v185, v21, 1.0 op_sel:[1,0,0]
	v_cvt_scalef32_pk_bf16_fp8 v201, v22, 1.0
	v_cvt_scalef32_pk_bf16_fp8 v202, v22, 1.0 op_sel:[1,0,0]
	v_cvt_scalef32_pk_bf16_fp8 v203, v23, 1.0
	v_cvt_scalef32_pk_bf16_fp8 v204, v23, 1.0 op_sel:[1,0,0]
	v_dot2_f32_bf16 v209, v182, v64, 0
	v_dot2_f32_bf16 v209, v183, v65, v209
	v_dot2_f32_bf16 v209, v184, v66, v209
	v_dot2_f32_bf16 v209, v185, v67, v209
	v_dot2_f32_bf16 v209, v201, v68, v209
	v_dot2_f32_bf16 v209, v202, v69, v209
	v_dot2_f32_bf16 v209, v203, v70, v209
	v_dot2_f32_bf16 v209, v204, v71, v209
	s_nop 2
	v_cvt_scalef32_pk_bf16_fp8 v184, v17, 1.0
	v_cvt_scalef32_pk_bf16_fp8 v182, v16, 1.0
	v_cvt_scalef32_pk_bf16_fp8 v183, v16, 1.0 op_sel:[1,0,0]
	v_cvt_scalef32_pk_bf16_fp8 v185, v17, 1.0 op_sel:[1,0,0]
	v_cvt_scalef32_pk_bf16_fp8 v201, v18, 1.0
	v_cvt_scalef32_pk_bf16_fp8 v202, v18, 1.0 op_sel:[1,0,0]
	v_cvt_scalef32_pk_bf16_fp8 v203, v19, 1.0
	v_cvt_scalef32_pk_bf16_fp8 v204, v19, 1.0 op_sel:[1,0,0]
	v_dot2_f32_bf16 v210, v182, v64, 0
	v_dot2_f32_bf16 v210, v183, v65, v210
	v_dot2_f32_bf16 v210, v184, v66, v210
	v_dot2_f32_bf16 v210, v185, v67, v210
	v_dot2_f32_bf16 v210, v201, v68, v210
	v_dot2_f32_bf16 v210, v202, v69, v210
	v_dot2_f32_bf16 v210, v203, v70, v210
	v_dot2_f32_bf16 v210, v204, v71, v210
	s_nop 2
	v_cvt_scalef32_pk_bf16_fp8 v184, v29, 1.0
	v_cvt_scalef32_pk_bf16_fp8 v182, v28, 1.0
	v_cvt_scalef32_pk_bf16_fp8 v183, v28, 1.0 op_sel:[1,0,0]
	v_cvt_scalef32_pk_bf16_fp8 v185, v29, 1.0 op_sel:[1,0,0]
	v_cvt_scalef32_pk_bf16_fp8 v201, v30, 1.0
	v_cvt_scalef32_pk_bf16_fp8 v202, v30, 1.0 op_sel:[1,0,0]
	v_cvt_scalef32_pk_bf16_fp8 v203, v31, 1.0
	v_cvt_scalef32_pk_bf16_fp8 v204, v31, 1.0 op_sel:[1,0,0]
	v_dot2_f32_bf16 v211, v182, v64, 0
	v_dot2_f32_bf16 v211, v183, v65, v211
	v_dot2_f32_bf16 v211, v184, v66, v211
	v_dot2_f32_bf16 v211, v185, v67, v211
	v_dot2_f32_bf16 v211, v201, v68, v211
	v_dot2_f32_bf16 v211, v202, v69, v211
	v_dot2_f32_bf16 v211, v203, v70, v211
	v_dot2_f32_bf16 v211, v204, v71, v211
	s_nop 2
	v_cvt_scalef32_pk_bf16_fp8 v184, v25, 1.0
	v_cvt_scalef32_pk_bf16_fp8 v182, v24, 1.0
	v_cvt_scalef32_pk_bf16_fp8 v183, v24, 1.0 op_sel:[1,0,0]
	v_cvt_scalef32_pk_bf16_fp8 v185, v25, 1.0 op_sel:[1,0,0]
	v_cvt_scalef32_pk_bf16_fp8 v201, v26, 1.0
	v_cvt_scalef32_pk_bf16_fp8 v202, v26, 1.0 op_sel:[1,0,0]
	v_cvt_scalef32_pk_bf16_fp8 v204, v27, 1.0
	v_cvt_scalef32_pk_bf16_fp8 v212, v27, 1.0 op_sel:[1,0,0]
	v_dot2_f32_bf16 v213, v182, v64, 0
	v_dot2_f32_bf16 v213, v183, v65, v213
	v_dot2_f32_bf16 v213, v184, v66, v213
	v_dot2_f32_bf16 v213, v185, v67, v213
	v_dot2_f32_bf16 v213, v201, v68, v213
	v_dot2_f32_bf16 v213, v202, v69, v213
	v_dot2_f32_bf16 v213, v204, v70, v213
	v_dot2_f32_bf16 v213, v212, v71, v213
	s_nop 2
	v_cndmask_b32_e64 v184, v206, v210, s[8:9]
	ds_bpermute_b32 v184, v193, v184
	v_cndmask_b32_e64 v185, v207, v211, s[8:9]
	v_cndmask_b32_e64 v203, v205, v209, s[8:9]
	ds_bpermute_b32 v185, v193, v185
	v_cndmask_b32_e64 v201, v208, v213, s[8:9]
	ds_bpermute_b32 v203, v193, v203
	ds_bpermute_b32 v201, v193, v201
	v_cndmask_b32_e64 v183, v210, v206, s[8:9]
	s_waitcnt lgkmcnt(3)
; DI float dot16(const unsigned (&a)[8], u32x4 b0, u32x4 b1) {
;     float acc;
;     asm volatile("v_dot2_f32_bf16 %0, %1, %9, 0\n\tv_dot2_f32_bf16 %0, %2, %10, %0\n\tv_dot2_f32_bf16 %0, %3, %11, %0\n\tv_dot2_f32_bf16 %0, %4, %12, %0\n\t"
;                  "v_dot2_f32_bf16 %0, %5, %13, %0\n\tv_dot2_f32_bf16 %0, %6, %14, %0\n\tv_dot2_f32_bf16 %0, %7, %15, %0\n\tv_dot2_f32_bf16 %0, %8, %16, %0\n\ts_nop 2"
;                  : "=&v"(acc)
;                  : "v"(a[0]), "v"(a[1]), "v"(a[2]), "v"(a[3]), "v"(a[4]), "v"(a[5]), "v"(a[6]), "v"(a[7]),
;                    "v"(b0.x), "v"(b0.y), "v"(b0.z), "v"(b0.w), "v"(b1.x), "v"(b1.y), "v"(b1.z), "v"(b1.w));
;     return acc;
; }
; DI float dot_fp8_row(u32x4 u, u32x4 xa, u32x4 xb) {
;     unsigned a[8];
; #pragma unroll
;     for (int j = 0; j < 4; ++j) {
;         a[2 * j] = __builtin_bit_cast(unsigned, __builtin_amdgcn_cvt_scalef32_pk_bf16_fp8(u[j], 1.0f, false));
;         a[2 * j + 1] = __builtin_bit_cast(unsigned, __builtin_amdgcn_cvt_scalef32_pk_bf16_fp8(u[j], 1.0f, true));
;     }
;     return dot16(a, xa, xb);
; }
	v_add_f32_e32 v183, v183, v184
	v_cndmask_b32_e64 v184, v211, v207, s[8:9]
	v_cndmask_b32_e64 v182, v209, v205, s[8:9]
	s_waitcnt lgkmcnt(2)
	v_add_f32_e32 v184, v184, v185
	v_cndmask_b32_e64 v185, v213, v208, s[8:9]
	s_waitcnt lgkmcnt(1)
	v_add_f32_e32 v182, v182, v203
	s_waitcnt lgkmcnt(0)
	v_add_f32_e32 v185, v185, v201
	v_cndmask_b32_e64 v201, v182, v184, s[10:11]
	v_cndmask_b32_e64 v202, v183, v185, s[10:11]
	ds_bpermute_b32 v201, v194, v201
	ds_bpermute_b32 v202, v194, v202
	v_cndmask_b32_e64 v182, v184, v182, s[10:11]
	v_cndmask_b32_e64 v183, v185, v183, s[10:11]
	v_cvt_scalef32_pk_bf16_fp8 v185, v36, 1.0
	s_waitcnt lgkmcnt(1)
	v_add_f32_e32 v182, v182, v201
	s_waitcnt lgkmcnt(0)
	v_add_f32_e32 v183, v183, v202
	v_cvt_scalef32_pk_bf16_fp8 v201, v36, 1.0 op_sel:[1,0,0]
	v_cvt_scalef32_pk_bf16_fp8 v202, v37, 1.0
	v_cvt_scalef32_pk_bf16_fp8 v203, v37, 1.0 op_sel:[1,0,0]
	v_cvt_scalef32_pk_bf16_fp8 v204, v38, 1.0
	v_cvt_scalef32_pk_bf16_fp8 v205, v38, 1.0 op_sel:[1,0,0]
	v_cvt_scalef32_pk_bf16_fp8 v207, v39, 1.0 op_sel:[1,0,0]
	v_cvt_scalef32_pk_bf16_fp8 v206, v39, 1.0
	v_dot2_f32_bf16 v208, v185, v64, 0
	v_dot2_f32_bf16 v208, v201, v65, v208
	v_dot2_f32_bf16 v208, v202, v66, v208
	v_dot2_f32_bf16 v208, v203, v67, v208
	v_dot2_f32_bf16 v208, v204, v68, v208
	v_dot2_f32_bf16 v208, v205, v69, v208
	v_dot2_f32_bf16 v208, v206, v70, v208
	v_dot2_f32_bf16 v208, v207, v71, v208
	s_nop 2
	v_cvt_scalef32_pk_bf16_fp8 v185, v32, 1.0
	v_cvt_scalef32_pk_bf16_fp8 v201, v32, 1.0 op_sel:[1,0,0]
	v_cvt_scalef32_pk_bf16_fp8 v202, v33, 1.0
	v_cvt_scalef32_pk_bf16_fp8 v203, v33, 1.0 op_sel:[1,0,0]
	v_cvt_scalef32_pk_bf16_fp8 v204, v34, 1.0
	v_cvt_scalef32_pk_bf16_fp8 v205, v34, 1.0 op_sel:[1,0,0]
	v_cvt_scalef32_pk_bf16_fp8 v207, v35, 1.0 op_sel:[1,0,0]
	v_cvt_scalef32_pk_bf16_fp8 v206, v35, 1.0
	v_dot2_f32_bf16 v209, v185, v64, 0
	v_dot2_f32_bf16 v209, v201, v65, v209
	v_dot2_f32_bf16 v209, v202, v66, v209
	v_dot2_f32_bf16 v209, v203, v67, v209
	v_dot2_f32_bf16 v209, v204, v68, v209
	v_dot2_f32_bf16 v209, v205, v69, v209
	v_dot2_f32_bf16 v209, v206, v70, v209
	v_dot2_f32_bf16 v209, v207, v71, v209
	s_nop 2
	v_cvt_scalef32_pk_bf16_fp8 v185, v44, 1.0
	v_cvt_scalef32_pk_bf16_fp8 v201, v44, 1.0 op_sel:[1,0,0]
	v_cvt_scalef32_pk_bf16_fp8 v202, v45, 1.0
	v_cvt_scalef32_pk_bf16_fp8 v203, v45, 1.0 op_sel:[1,0,0]
	v_cvt_scalef32_pk_bf16_fp8 v204, v46, 1.0
	v_cvt_scalef32_pk_bf16_fp8 v205, v46, 1.0 op_sel:[1,0,0]
	v_cvt_scalef32_pk_bf16_fp8 v207, v47, 1.0 op_sel:[1,0,0]
	v_cvt_scalef32_pk_bf16_fp8 v206, v47, 1.0
	v_dot2_f32_bf16 v210, v185, v64, 0
	v_dot2_f32_bf16 v210, v201, v65, v210
	v_dot2_f32_bf16 v210, v202, v66, v210
	v_dot2_f32_bf16 v210, v203, v67, v210
	v_dot2_f32_bf16 v210, v204, v68, v210
	v_dot2_f32_bf16 v210, v205, v69, v210
	v_dot2_f32_bf16 v210, v206, v70, v210
	v_dot2_f32_bf16 v210, v207, v71, v210
	s_nop 2
	v_cvt_scalef32_pk_bf16_fp8 v185, v40, 1.0
	v_cvt_scalef32_pk_bf16_fp8 v201, v40, 1.0 op_sel:[1,0,0]
	v_cvt_scalef32_pk_bf16_fp8 v202, v41, 1.0
	v_cvt_scalef32_pk_bf16_fp8 v203, v41, 1.0 op_sel:[1,0,0]
	v_cvt_scalef32_pk_bf16_fp8 v204, v42, 1.0
	v_cvt_scalef32_pk_bf16_fp8 v205, v42, 1.0 op_sel:[1,0,0]
	v_cvt_scalef32_pk_bf16_fp8 v207, v43, 1.0 op_sel:[1,0,0]
	v_cvt_scalef32_pk_bf16_fp8 v206, v43, 1.0
	v_dot2_f32_bf16 v211, v185, v64, 0
	v_dot2_f32_bf16 v211, v201, v65, v211
	v_dot2_f32_bf16 v211, v202, v66, v211
	v_dot2_f32_bf16 v211, v203, v67, v211
	v_dot2_f32_bf16 v211, v204, v68, v211
	v_dot2_f32_bf16 v211, v205, v69, v211
	v_dot2_f32_bf16 v211, v206, v70, v211
	v_dot2_f32_bf16 v211, v207, v71, v211
	s_nop 2
	v_cvt_scalef32_pk_bf16_fp8 v185, v52, 1.0
	v_cvt_scalef32_pk_bf16_fp8 v201, v52, 1.0 op_sel:[1,0,0]
	v_cvt_scalef32_pk_bf16_fp8 v202, v53, 1.0
	v_cvt_scalef32_pk_bf16_fp8 v203, v53, 1.0 op_sel:[1,0,0]
	v_cvt_scalef32_pk_bf16_fp8 v204, v54, 1.0
	v_cvt_scalef32_pk_bf16_fp8 v205, v54, 1.0 op_sel:[1,0,0]
	v_cvt_scalef32_pk_bf16_fp8 v207, v55, 1.0 op_sel:[1,0,0]
	v_cvt_scalef32_pk_bf16_fp8 v206, v55, 1.0
	v_dot2_f32_bf16 v212, v185, v64, 0
	v_dot2_f32_bf16 v212, v201, v65, v212
	v_dot2_f32_bf16 v212, v202, v66, v212
	v_dot2_f32_bf16 v212, v203, v67, v212
	v_dot2_f32_bf16 v212, v204, v68, v212
	v_dot2_f32_bf16 v212, v205, v69, v212
	v_dot2_f32_bf16 v212, v206, v70, v212
	v_dot2_f32_bf16 v212, v207, v71, v212
	s_nop 2
	v_cvt_scalef32_pk_bf16_fp8 v185, v48, 1.0
	v_cvt_scalef32_pk_bf16_fp8 v201, v48, 1.0 op_sel:[1,0,0]
	v_cvt_scalef32_pk_bf16_fp8 v202, v49, 1.0
	v_cvt_scalef32_pk_bf16_fp8 v203, v49, 1.0 op_sel:[1,0,0]
	v_cvt_scalef32_pk_bf16_fp8 v204, v50, 1.0
	v_cvt_scalef32_pk_bf16_fp8 v205, v50, 1.0 op_sel:[1,0,0]
	v_cvt_scalef32_pk_bf16_fp8 v207, v51, 1.0 op_sel:[1,0,0]
	v_cvt_scalef32_pk_bf16_fp8 v206, v51, 1.0
	v_dot2_f32_bf16 v213, v185, v64, 0
	v_dot2_f32_bf16 v213, v201, v65, v213
	v_dot2_f32_bf16 v213, v202, v66, v213
	v_dot2_f32_bf16 v213, v203, v67, v213
	v_dot2_f32_bf16 v213, v204, v68, v213
	v_dot2_f32_bf16 v213, v205, v69, v213
	v_dot2_f32_bf16 v213, v206, v70, v213
	v_dot2_f32_bf16 v213, v207, v71, v213
	s_nop 2
	v_cvt_scalef32_pk_bf16_fp8 v185, v60, 1.0
	v_cvt_scalef32_pk_bf16_fp8 v201, v60, 1.0 op_sel:[1,0,0]
	v_cvt_scalef32_pk_bf16_fp8 v202, v61, 1.0
	v_cvt_scalef32_pk_bf16_fp8 v203, v61, 1.0 op_sel:[1,0,0]
	v_cvt_scalef32_pk_bf16_fp8 v204, v62, 1.0
	v_cvt_scalef32_pk_bf16_fp8 v205, v62, 1.0 op_sel:[1,0,0]
	v_cvt_scalef32_pk_bf16_fp8 v207, v63, 1.0 op_sel:[1,0,0]
	v_cvt_scalef32_pk_bf16_fp8 v206, v63, 1.0
	v_dot2_f32_bf16 v214, v185, v64, 0
	v_dot2_f32_bf16 v214, v201, v65, v214
	v_dot2_f32_bf16 v214, v202, v66, v214
	v_dot2_f32_bf16 v214, v203, v67, v214
	v_dot2_f32_bf16 v214, v204, v68, v214
	v_dot2_f32_bf16 v214, v205, v69, v214
	v_dot2_f32_bf16 v214, v206, v70, v214
	v_dot2_f32_bf16 v214, v207, v71, v214
	s_nop 2
	v_cvt_scalef32_pk_bf16_fp8 v185, v56, 1.0
	v_cvt_scalef32_pk_bf16_fp8 v201, v56, 1.0 op_sel:[1,0,0]
	v_cvt_scalef32_pk_bf16_fp8 v202, v57, 1.0
	v_cvt_scalef32_pk_bf16_fp8 v203, v57, 1.0 op_sel:[1,0,0]
	v_cvt_scalef32_pk_bf16_fp8 v204, v58, 1.0
	v_cvt_scalef32_pk_bf16_fp8 v205, v58, 1.0 op_sel:[1,0,0]
	v_cvt_scalef32_pk_bf16_fp8 v207, v59, 1.0
	v_cvt_scalef32_pk_bf16_fp8 v215, v59, 1.0 op_sel:[1,0,0]
	v_dot2_f32_bf16 v216, v185, v64, 0
	v_dot2_f32_bf16 v216, v201, v65, v216
	v_dot2_f32_bf16 v216, v202, v66, v216
	v_dot2_f32_bf16 v216, v203, v67, v216
	v_dot2_f32_bf16 v216, v204, v68, v216
	v_dot2_f32_bf16 v216, v205, v69, v216
	v_dot2_f32_bf16 v216, v207, v70, v216
	v_dot2_f32_bf16 v216, v215, v71, v216
	s_nop 2
	v_cndmask_b32_e64 v66, v209, v213, s[8:9]
	ds_bpermute_b32 v66, v193, v66
	v_cndmask_b32_e64 v67, v210, v214, s[8:9]
	v_cndmask_b32_e64 v206, v208, v212, s[8:9]
	ds_bpermute_b32 v67, v193, v67
	v_cndmask_b32_e64 v68, v211, v216, s[8:9]
	ds_bpermute_b32 v206, v193, v206
	ds_bpermute_b32 v68, v193, v68
	v_cndmask_b32_e64 v65, v213, v209, s[8:9]
	s_waitcnt lgkmcnt(3)
	v_add_f32_e32 v65, v65, v66
	v_cndmask_b32_e64 v66, v214, v210, s[8:9]
	v_cndmask_b32_e64 v64, v212, v208, s[8:9]
	s_waitcnt lgkmcnt(2)
	v_add_f32_e32 v66, v66, v67
	v_cndmask_b32_e64 v67, v216, v211, s[8:9]
	s_waitcnt lgkmcnt(1)
	v_add_f32_e32 v64, v64, v206
	s_waitcnt lgkmcnt(0)
	v_add_f32_e32 v67, v67, v68
	v_cndmask_b32_e64 v68, v64, v66, s[10:11]
	v_cndmask_b32_e64 v69, v65, v67, s[10:11]
	ds_bpermute_b32 v68, v194, v68
	ds_bpermute_b32 v69, v194, v69
	v_cndmask_b32_e64 v64, v66, v64, s[10:11]
	v_cndmask_b32_e64 v65, v67, v65, s[10:11]
	v_cndmask_b32_e64 v184, v182, v183, s[12:13]
	s_waitcnt lgkmcnt(1)
	v_add_f32_e32 v64, v64, v68
	s_waitcnt lgkmcnt(0)
	v_add_f32_e32 v65, v65, v69
	v_cndmask_b32_e64 v66, v64, v65, s[12:13]
	ds_bpermute_b32 v70, v195, v184
	ds_bpermute_b32 v66, v195, v66
	v_cndmask_b32_e64 v67, v183, v182, s[12:13]
	v_cndmask_b32_e64 v64, v65, v64, s[12:13]
	s_waitcnt lgkmcnt(1)
	v_add_f32_e32 v67, v67, v70
	s_waitcnt lgkmcnt(0)
	v_add_f32_e32 v66, v64, v66
	s_setprio 0
	v_lshlrev_b64 v[64:65], 12, v[180:181]
	v_lshl_add_u64 v[64:65], v[178:179], 0, v[64:65]
	global_store_dword v[64:65], v67, off
	global_store_dword v[64:65], v66, off offset:256
	s_waitcnt vmcnt(2)
	v_mov_b64_e32 v[64:65], v[72:73]
	v_mov_b64_e32 v[68:69], v[140:141]
	v_mov_b64_e32 v[66:67], v[74:75]
	v_mov_b64_e32 v[70:71], v[142:143]

; DI float dot16(const unsigned (&a)[8], u32x4 b0, u32x4 b1) {
;     float acc;
;     asm volatile("v_dot2_f32_bf16 %0, %1, %9, 0\n\tv_dot2_f32_bf16 %0, %2, %10, %0\n\tv_dot2_f32_bf16 %0, %3, %11, %0\n\tv_dot2_f32_bf16 %0, %4, %12, %0\n\t"
;                  "v_dot2_f32_bf16 %0, %5, %13, %0\n\tv_dot2_f32_bf16 %0, %6, %14, %0\n\tv_dot2_f32_bf16 %0, %7, %15, %0\n\tv_dot2_f32_bf16 %0, %8, %16, %0\n\ts_nop 2"
;                  : "=&v"(acc)
;                  : "v"(a[0]), "v"(a[1]), "v"(a[2]), "v"(a[3]), "v"(a[4]), "v"(a[5]), "v"(a[6]), "v"(a[7]),
;                    "v"(b0.x), "v"(b0.y), "v"(b0.z), "v"(b0.w), "v"(b1.x), "v"(b1.y), "v"(b1.z), "v"(b1.w));
;     return acc;
; }
; DI float dot_fp8_row(u32x4 u, u32x4 xa, u32x4 xb) {
;     unsigned a[8];
; #pragma unroll
;     for (int j = 0; j < 4; ++j) {
;         a[2 * j] = __builtin_bit_cast(unsigned, __builtin_amdgcn_cvt_scalef32_pk_bf16_fp8(u[j], 1.0f, false));
;         a[2 * j + 1] = __builtin_bit_cast(unsigned, __builtin_amdgcn_cvt_scalef32_pk_bf16_fp8(u[j], 1.0f, true));
;     }
;     return dot16(a, xa, xb);
; }
.LBB0_1233:
	s_or_b64 exec, exec, s[0:1]
	s_setprio 1
	s_waitcnt vmcnt(15)
	v_cvt_scalef32_pk_bf16_fp8 v203, v77, 1.0
	v_cvt_scalef32_pk_bf16_fp8 v183, v76, 1.0
	v_cvt_scalef32_pk_bf16_fp8 v202, v76, 1.0 op_sel:[1,0,0]
	v_cvt_scalef32_pk_bf16_fp8 v204, v77, 1.0 op_sel:[1,0,0]
	v_cvt_scalef32_pk_bf16_fp8 v205, v78, 1.0
	v_cvt_scalef32_pk_bf16_fp8 v206, v78, 1.0 op_sel:[1,0,0]
	v_cvt_scalef32_pk_bf16_fp8 v207, v79, 1.0
	v_cvt_scalef32_pk_bf16_fp8 v208, v79, 1.0 op_sel:[1,0,0]
	v_dot2_f32_bf16 v209, v183, v72, 0
	v_dot2_f32_bf16 v209, v202, v73, v209
	v_dot2_f32_bf16 v209, v203, v74, v209
	v_dot2_f32_bf16 v209, v204, v75, v209
	v_dot2_f32_bf16 v209, v205, v140, v209
	v_dot2_f32_bf16 v209, v206, v141, v209
	v_dot2_f32_bf16 v209, v207, v142, v209
	v_dot2_f32_bf16 v209, v208, v143, v209
	s_nop 2
	s_waitcnt vmcnt(14)
	v_cvt_scalef32_pk_bf16_fp8 v203, v81, 1.0
	v_cvt_scalef32_pk_bf16_fp8 v183, v80, 1.0
	v_cvt_scalef32_pk_bf16_fp8 v202, v80, 1.0 op_sel:[1,0,0]
	v_cvt_scalef32_pk_bf16_fp8 v204, v81, 1.0 op_sel:[1,0,0]
	v_cvt_scalef32_pk_bf16_fp8 v205, v82, 1.0
	v_cvt_scalef32_pk_bf16_fp8 v206, v82, 1.0 op_sel:[1,0,0]
	v_cvt_scalef32_pk_bf16_fp8 v207, v83, 1.0
	v_cvt_scalef32_pk_bf16_fp8 v208, v83, 1.0 op_sel:[1,0,0]
	v_dot2_f32_bf16 v210, v183, v72, 0
	v_dot2_f32_bf16 v210, v202, v73, v210
	v_dot2_f32_bf16 v210, v203, v74, v210
	v_dot2_f32_bf16 v210, v204, v75, v210
	v_dot2_f32_bf16 v210, v205, v140, v210
	v_dot2_f32_bf16 v210, v206, v141, v210
	v_dot2_f32_bf16 v210, v207, v142, v210
	v_dot2_f32_bf16 v210, v208, v143, v210
	s_nop 2
	s_waitcnt vmcnt(13)
	v_cvt_scalef32_pk_bf16_fp8 v203, v85, 1.0
	v_cvt_scalef32_pk_bf16_fp8 v183, v84, 1.0
	v_cvt_scalef32_pk_bf16_fp8 v202, v84, 1.0 op_sel:[1,0,0]
	v_cvt_scalef32_pk_bf16_fp8 v204, v85, 1.0 op_sel:[1,0,0]
	v_cvt_scalef32_pk_bf16_fp8 v205, v86, 1.0
	v_cvt_scalef32_pk_bf16_fp8 v206, v86, 1.0 op_sel:[1,0,0]
	v_cvt_scalef32_pk_bf16_fp8 v207, v87, 1.0
	v_cvt_scalef32_pk_bf16_fp8 v208, v87, 1.0 op_sel:[1,0,0]
	v_dot2_f32_bf16 v211, v183, v72, 0
	v_dot2_f32_bf16 v211, v202, v73, v211
	v_dot2_f32_bf16 v211, v203, v74, v211
	v_dot2_f32_bf16 v211, v204, v75, v211
	v_dot2_f32_bf16 v211, v205, v140, v211
	v_dot2_f32_bf16 v211, v206, v141, v211
	v_dot2_f32_bf16 v211, v207, v142, v211
	v_dot2_f32_bf16 v211, v208, v143, v211
	s_nop 2
	s_waitcnt vmcnt(12)
	v_cvt_scalef32_pk_bf16_fp8 v203, v89, 1.0
	v_cvt_scalef32_pk_bf16_fp8 v183, v88, 1.0
	v_cvt_scalef32_pk_bf16_fp8 v202, v88, 1.0 op_sel:[1,0,0]
	v_cvt_scalef32_pk_bf16_fp8 v204, v89, 1.0 op_sel:[1,0,0]
	v_cvt_scalef32_pk_bf16_fp8 v205, v90, 1.0
	v_cvt_scalef32_pk_bf16_fp8 v206, v90, 1.0 op_sel:[1,0,0]
	v_cvt_scalef32_pk_bf16_fp8 v207, v91, 1.0
	v_cvt_scalef32_pk_bf16_fp8 v208, v91, 1.0 op_sel:[1,0,0]
	v_dot2_f32_bf16 v212, v183, v72, 0
	v_dot2_f32_bf16 v212, v202, v73, v212
	v_dot2_f32_bf16 v212, v203, v74, v212
	v_dot2_f32_bf16 v212, v204, v75, v212
	v_dot2_f32_bf16 v212, v205, v140, v212
	v_dot2_f32_bf16 v212, v206, v141, v212
	v_dot2_f32_bf16 v212, v207, v142, v212
	v_dot2_f32_bf16 v212, v208, v143, v212
	s_nop 2
	s_waitcnt vmcnt(11)
	v_cvt_scalef32_pk_bf16_fp8 v203, v93, 1.0
	v_cvt_scalef32_pk_bf16_fp8 v183, v92, 1.0
	v_cvt_scalef32_pk_bf16_fp8 v202, v92, 1.0 op_sel:[1,0,0]
	v_cvt_scalef32_pk_bf16_fp8 v204, v93, 1.0 op_sel:[1,0,0]
	v_cvt_scalef32_pk_bf16_fp8 v205, v94, 1.0
	v_cvt_scalef32_pk_bf16_fp8 v206, v94, 1.0 op_sel:[1,0,0]
	v_cvt_scalef32_pk_bf16_fp8 v207, v95, 1.0
	v_cvt_scalef32_pk_bf16_fp8 v208, v95, 1.0 op_sel:[1,0,0]
	v_dot2_f32_bf16 v213, v183, v72, 0
	v_dot2_f32_bf16 v213, v202, v73, v213
	v_dot2_f32_bf16 v213, v203, v74, v213
	v_dot2_f32_bf16 v213, v204, v75, v213
	v_dot2_f32_bf16 v213, v205, v140, v213
	v_dot2_f32_bf16 v213, v206, v141, v213
	v_dot2_f32_bf16 v213, v207, v142, v213
	v_dot2_f32_bf16 v213, v208, v143, v213
	s_nop 2
	s_waitcnt vmcnt(10)
	v_cvt_scalef32_pk_bf16_fp8 v203, v97, 1.0
	v_cvt_scalef32_pk_bf16_fp8 v183, v96, 1.0
	v_cvt_scalef32_pk_bf16_fp8 v202, v96, 1.0 op_sel:[1,0,0]
	v_cvt_scalef32_pk_bf16_fp8 v204, v97, 1.0 op_sel:[1,0,0]
	v_cvt_scalef32_pk_bf16_fp8 v205, v98, 1.0
	v_cvt_scalef32_pk_bf16_fp8 v206, v98, 1.0 op_sel:[1,0,0]
	v_cvt_scalef32_pk_bf16_fp8 v207, v99, 1.0
	v_cvt_scalef32_pk_bf16_fp8 v208, v99, 1.0 op_sel:[1,0,0]
	v_dot2_f32_bf16 v214, v183, v72, 0
	v_dot2_f32_bf16 v214, v202, v73, v214
	v_dot2_f32_bf16 v214, v203, v74, v214
	v_dot2_f32_bf16 v214, v204, v75, v214
	v_dot2_f32_bf16 v214, v205, v140, v214
	v_dot2_f32_bf16 v214, v206, v141, v214
	v_dot2_f32_bf16 v214, v207, v142, v214
	v_dot2_f32_bf16 v214, v208, v143, v214
	s_nop 2
	s_waitcnt vmcnt(9)
	v_cvt_scalef32_pk_bf16_fp8 v203, v101, 1.0
	v_cvt_scalef32_pk_bf16_fp8 v183, v100, 1.0
	v_cvt_scalef32_pk_bf16_fp8 v202, v100, 1.0 op_sel:[1,0,0]
	v_cvt_scalef32_pk_bf16_fp8 v204, v101, 1.0 op_sel:[1,0,0]
	v_cvt_scalef32_pk_bf16_fp8 v205, v102, 1.0
	v_cvt_scalef32_pk_bf16_fp8 v206, v102, 1.0 op_sel:[1,0,0]
	v_cvt_scalef32_pk_bf16_fp8 v207, v103, 1.0
	v_cvt_scalef32_pk_bf16_fp8 v208, v103, 1.0 op_sel:[1,0,0]
	v_dot2_f32_bf16 v215, v183, v72, 0
	v_dot2_f32_bf16 v215, v202, v73, v215
	v_dot2_f32_bf16 v215, v203, v74, v215
	v_dot2_f32_bf16 v215, v204, v75, v215
	v_dot2_f32_bf16 v215, v205, v140, v215
	v_dot2_f32_bf16 v215, v206, v141, v215
	v_dot2_f32_bf16 v215, v207, v142, v215
	v_dot2_f32_bf16 v215, v208, v143, v215
	s_nop 2
	s_waitcnt vmcnt(8)
; DI float dot16(const unsigned (&a)[8], u32x4 b0, u32x4 b1) {
;     float acc;
;     asm volatile("v_dot2_f32_bf16 %0, %1, %9, 0\n\tv_dot2_f32_bf16 %0, %2, %10, %0\n\tv_dot2_f32_bf16 %0, %3, %11, %0\n\tv_dot2_f32_bf16 %0, %4, %12, %0\n\t"
;                  "v_dot2_f32_bf16 %0, %5, %13, %0\n\tv_dot2_f32_bf16 %0, %6, %14, %0\n\tv_dot2_f32_bf16 %0, %7, %15, %0\n\tv_dot2_f32_bf16 %0, %8, %16, %0\n\ts_nop 2"
;                  : "=&v"(acc)
;                  : "v"(a[0]), "v"(a[1]), "v"(a[2]), "v"(a[3]), "v"(a[4]), "v"(a[5]), "v"(a[6]), "v"(a[7]),
;                    "v"(b0.x), "v"(b0.y), "v"(b0.z), "v"(b0.w), "v"(b1.x), "v"(b1.y), "v"(b1.z), "v"(b1.w));
;     return acc;
; }
; DI float dot_fp8_row(u32x4 u, u32x4 xa, u32x4 xb) {
;     unsigned a[8];
; #pragma unroll
;     for (int j = 0; j < 4; ++j) {
;         a[2 * j] = __builtin_bit_cast(unsigned, __builtin_amdgcn_cvt_scalef32_pk_bf16_fp8(u[j], 1.0f, false));
;         a[2 * j + 1] = __builtin_bit_cast(unsigned, __builtin_amdgcn_cvt_scalef32_pk_bf16_fp8(u[j], 1.0f, true));
;     }
;     return dot16(a, xa, xb);
; }
	v_cvt_scalef32_pk_bf16_fp8 v203, v105, 1.0
	v_cvt_scalef32_pk_bf16_fp8 v183, v104, 1.0
	v_cvt_scalef32_pk_bf16_fp8 v202, v104, 1.0 op_sel:[1,0,0]
	v_cvt_scalef32_pk_bf16_fp8 v204, v105, 1.0 op_sel:[1,0,0]
	v_cvt_scalef32_pk_bf16_fp8 v205, v106, 1.0
	v_cvt_scalef32_pk_bf16_fp8 v206, v106, 1.0 op_sel:[1,0,0]
	v_cvt_scalef32_pk_bf16_fp8 v208, v107, 1.0
	v_cvt_scalef32_pk_bf16_fp8 v216, v107, 1.0 op_sel:[1,0,0]
	v_dot2_f32_bf16 v217, v183, v72, 0
	v_dot2_f32_bf16 v217, v202, v73, v217
	v_dot2_f32_bf16 v217, v203, v74, v217
	v_dot2_f32_bf16 v217, v204, v75, v217
	v_dot2_f32_bf16 v217, v205, v140, v217
	v_dot2_f32_bf16 v217, v206, v141, v217
	v_dot2_f32_bf16 v217, v208, v142, v217
	v_dot2_f32_bf16 v217, v216, v143, v217
	s_nop 2
	v_cndmask_b32_e64 v203, v210, v214, s[8:9]
	ds_bpermute_b32 v203, v193, v203
	v_cndmask_b32_e64 v204, v211, v215, s[8:9]
	ds_bpermute_b32 v204, v193, v204
	v_cndmask_b32_e64 v205, v212, v217, s[8:9]
	v_cndmask_b32_e64 v207, v209, v213, s[8:9]
	ds_bpermute_b32 v205, v193, v205
	ds_bpermute_b32 v207, v193, v207
	v_cndmask_b32_e64 v202, v214, v210, s[8:9]
	s_waitcnt lgkmcnt(3)
	v_add_f32_e32 v202, v202, v203
	v_cndmask_b32_e64 v203, v215, v211, s[8:9]
	s_waitcnt lgkmcnt(2)
	v_add_f32_e32 v203, v203, v204
	v_cndmask_b32_e64 v204, v217, v212, s[8:9]
	v_cndmask_b32_e64 v183, v213, v209, s[8:9]
	s_waitcnt lgkmcnt(1)
	v_add_f32_e32 v204, v204, v205
	s_waitcnt lgkmcnt(0)
	v_add_f32_e32 v183, v183, v207
	v_cndmask_b32_e64 v206, v202, v204, s[10:11]
	v_cndmask_b32_e64 v205, v183, v203, s[10:11]
	ds_bpermute_b32 v206, v194, v206
	ds_bpermute_b32 v205, v194, v205
	v_cndmask_b32_e64 v202, v204, v202, s[10:11]
	v_cndmask_b32_e64 v183, v203, v183, s[10:11]
	s_waitcnt vmcnt(7)
	v_cvt_scalef32_pk_bf16_fp8 v204, v108, 1.0
	s_waitcnt lgkmcnt(1)
	v_add_f32_e32 v202, v202, v206
	v_cvt_scalef32_pk_bf16_fp8 v206, v109, 1.0
	s_waitcnt lgkmcnt(0)
	v_add_f32_e32 v183, v183, v205
	v_cvt_scalef32_pk_bf16_fp8 v205, v108, 1.0 op_sel:[1,0,0]
	v_cvt_scalef32_pk_bf16_fp8 v207, v109, 1.0 op_sel:[1,0,0]
	v_cvt_scalef32_pk_bf16_fp8 v208, v110, 1.0
	v_cvt_scalef32_pk_bf16_fp8 v209, v110, 1.0 op_sel:[1,0,0]
	v_cvt_scalef32_pk_bf16_fp8 v210, v111, 1.0
	v_cvt_scalef32_pk_bf16_fp8 v211, v111, 1.0 op_sel:[1,0,0]
	v_dot2_f32_bf16 v212, v204, v72, 0
	v_dot2_f32_bf16 v212, v205, v73, v212
	v_dot2_f32_bf16 v212, v206, v74, v212
	v_dot2_f32_bf16 v212, v207, v75, v212
	v_dot2_f32_bf16 v212, v208, v140, v212
	v_dot2_f32_bf16 v212, v209, v141, v212
	v_dot2_f32_bf16 v212, v210, v142, v212
	v_dot2_f32_bf16 v212, v211, v143, v212
	s_nop 2
	s_waitcnt vmcnt(6)
	v_cvt_scalef32_pk_bf16_fp8 v206, v113, 1.0
	v_cvt_scalef32_pk_bf16_fp8 v204, v112, 1.0
	v_cvt_scalef32_pk_bf16_fp8 v205, v112, 1.0 op_sel:[1,0,0]
	v_cvt_scalef32_pk_bf16_fp8 v207, v113, 1.0 op_sel:[1,0,0]
	v_cvt_scalef32_pk_bf16_fp8 v208, v114, 1.0
	v_cvt_scalef32_pk_bf16_fp8 v209, v114, 1.0 op_sel:[1,0,0]
	v_cvt_scalef32_pk_bf16_fp8 v210, v115, 1.0
	v_cvt_scalef32_pk_bf16_fp8 v211, v115, 1.0 op_sel:[1,0,0]
	v_dot2_f32_bf16 v213, v204, v72, 0
	v_dot2_f32_bf16 v213, v205, v73, v213
	v_dot2_f32_bf16 v213, v206, v74, v213
	v_dot2_f32_bf16 v213, v207, v75, v213
	v_dot2_f32_bf16 v213, v208, v140, v213
	v_dot2_f32_bf16 v213, v209, v141, v213
	v_dot2_f32_bf16 v213, v210, v142, v213
	v_dot2_f32_bf16 v213, v211, v143, v213
	s_nop 2
	s_waitcnt vmcnt(5)
	v_cvt_scalef32_pk_bf16_fp8 v206, v117, 1.0
	v_cvt_scalef32_pk_bf16_fp8 v204, v116, 1.0
	v_cvt_scalef32_pk_bf16_fp8 v205, v116, 1.0 op_sel:[1,0,0]
	v_cvt_scalef32_pk_bf16_fp8 v207, v117, 1.0 op_sel:[1,0,0]
	v_cvt_scalef32_pk_bf16_fp8 v208, v118, 1.0
	v_cvt_scalef32_pk_bf16_fp8 v209, v118, 1.0 op_sel:[1,0,0]
	v_cvt_scalef32_pk_bf16_fp8 v210, v119, 1.0
	v_cvt_scalef32_pk_bf16_fp8 v211, v119, 1.0 op_sel:[1,0,0]
	v_dot2_f32_bf16 v214, v204, v72, 0
	v_dot2_f32_bf16 v214, v205, v73, v214
	v_dot2_f32_bf16 v214, v206, v74, v214
	v_dot2_f32_bf16 v214, v207, v75, v214
	v_dot2_f32_bf16 v214, v208, v140, v214
	v_dot2_f32_bf16 v214, v209, v141, v214
	v_dot2_f32_bf16 v214, v210, v142, v214
	v_dot2_f32_bf16 v214, v211, v143, v214
	s_nop 2
	s_waitcnt vmcnt(4)
	v_cvt_scalef32_pk_bf16_fp8 v206, v121, 1.0
	v_cvt_scalef32_pk_bf16_fp8 v204, v120, 1.0
	v_cvt_scalef32_pk_bf16_fp8 v205, v120, 1.0 op_sel:[1,0,0]
	v_cvt_scalef32_pk_bf16_fp8 v207, v121, 1.0 op_sel:[1,0,0]
	v_cvt_scalef32_pk_bf16_fp8 v208, v122, 1.0
	v_cvt_scalef32_pk_bf16_fp8 v209, v122, 1.0 op_sel:[1,0,0]
	v_cvt_scalef32_pk_bf16_fp8 v210, v123, 1.0
	v_cvt_scalef32_pk_bf16_fp8 v211, v123, 1.0 op_sel:[1,0,0]
	v_dot2_f32_bf16 v215, v204, v72, 0
	v_dot2_f32_bf16 v215, v205, v73, v215
	v_dot2_f32_bf16 v215, v206, v74, v215
	v_dot2_f32_bf16 v215, v207, v75, v215
	v_dot2_f32_bf16 v215, v208, v140, v215
	v_dot2_f32_bf16 v215, v209, v141, v215
	v_dot2_f32_bf16 v215, v210, v142, v215
	v_dot2_f32_bf16 v215, v211, v143, v215
	s_nop 2
	s_waitcnt vmcnt(3)
	v_cvt_scalef32_pk_bf16_fp8 v206, v125, 1.0
	v_cvt_scalef32_pk_bf16_fp8 v204, v124, 1.0
	v_cvt_scalef32_pk_bf16_fp8 v205, v124, 1.0 op_sel:[1,0,0]
	v_cvt_scalef32_pk_bf16_fp8 v207, v125, 1.0 op_sel:[1,0,0]
	v_cvt_scalef32_pk_bf16_fp8 v208, v126, 1.0
	v_cvt_scalef32_pk_bf16_fp8 v209, v126, 1.0 op_sel:[1,0,0]
	v_cvt_scalef32_pk_bf16_fp8 v210, v127, 1.0
	v_cvt_scalef32_pk_bf16_fp8 v211, v127, 1.0 op_sel:[1,0,0]
	v_dot2_f32_bf16 v216, v204, v72, 0
	v_dot2_f32_bf16 v216, v205, v73, v216
	v_dot2_f32_bf16 v216, v206, v74, v216
	v_dot2_f32_bf16 v216, v207, v75, v216
	v_dot2_f32_bf16 v216, v208, v140, v216
	v_dot2_f32_bf16 v216, v209, v141, v216
	v_dot2_f32_bf16 v216, v210, v142, v216
	v_dot2_f32_bf16 v216, v211, v143, v216
	s_nop 2
	s_waitcnt vmcnt(2)
; #define U_ISSUE(SEG, E0, E1) { _Pragma("unroll") for (int b = 0; b < 16; ++b) { const int e = __shfl((b < 8) ? (E0) : (E1), (b & 7) * 8 + grp); SEG[b] = *(const u32x4*)(ub + (size_t)e * DM); } }
; DI void peer_u_phase(const bf16_t* __restrict__ x1, const int* __restrict__ eidx, const unsigned char* __restrict__ U8, float* __restrict__ ph) {
;     ...
;             if (n1) {
;                 xa = xan; xb = xbn;
;                 if (n2) { U_ISSUE(sa, e0nn, e1nn) xan = *(const u32x4*)(xb_ + (size_t)(t + 2 * step) * DM); xbn = *(const u32x4*)(xb_ + (size_t)(t + 2 * step) * DM + 8); }
	v_cvt_scalef32_pk_bf16_fp8 v206, v129, 1.0
	v_cvt_scalef32_pk_bf16_fp8 v204, v128, 1.0
	v_cvt_scalef32_pk_bf16_fp8 v205, v128, 1.0 op_sel:[1,0,0]
	v_cvt_scalef32_pk_bf16_fp8 v207, v129, 1.0 op_sel:[1,0,0]
	v_cvt_scalef32_pk_bf16_fp8 v208, v130, 1.0
	v_cvt_scalef32_pk_bf16_fp8 v209, v130, 1.0 op_sel:[1,0,0]
	v_cvt_scalef32_pk_bf16_fp8 v210, v131, 1.0
	v_cvt_scalef32_pk_bf16_fp8 v211, v131, 1.0 op_sel:[1,0,0]
	v_dot2_f32_bf16 v217, v204, v72, 0
	v_dot2_f32_bf16 v217, v205, v73, v217
	v_dot2_f32_bf16 v217, v206, v74, v217
	v_dot2_f32_bf16 v217, v207, v75, v217
	v_dot2_f32_bf16 v217, v208, v140, v217
	v_dot2_f32_bf16 v217, v209, v141, v217
	v_dot2_f32_bf16 v217, v210, v142, v217
	v_dot2_f32_bf16 v217, v211, v143, v217
	s_nop 2
	s_waitcnt vmcnt(1)
	v_cvt_scalef32_pk_bf16_fp8 v206, v133, 1.0
	v_cvt_scalef32_pk_bf16_fp8 v204, v132, 1.0
	v_cvt_scalef32_pk_bf16_fp8 v205, v132, 1.0 op_sel:[1,0,0]
	v_cvt_scalef32_pk_bf16_fp8 v207, v133, 1.0 op_sel:[1,0,0]
	v_cvt_scalef32_pk_bf16_fp8 v208, v134, 1.0
	v_cvt_scalef32_pk_bf16_fp8 v209, v134, 1.0 op_sel:[1,0,0]
	v_cvt_scalef32_pk_bf16_fp8 v210, v135, 1.0
	v_cvt_scalef32_pk_bf16_fp8 v211, v135, 1.0 op_sel:[1,0,0]
	v_dot2_f32_bf16 v218, v204, v72, 0
	v_dot2_f32_bf16 v218, v205, v73, v218
	v_dot2_f32_bf16 v218, v206, v74, v218
	v_dot2_f32_bf16 v218, v207, v75, v218
	v_dot2_f32_bf16 v218, v208, v140, v218
	v_dot2_f32_bf16 v218, v209, v141, v218
	v_dot2_f32_bf16 v218, v210, v142, v218
	v_dot2_f32_bf16 v218, v211, v143, v218
	s_nop 2
	s_waitcnt vmcnt(0)
	v_cvt_scalef32_pk_bf16_fp8 v206, v137, 1.0
	v_cvt_scalef32_pk_bf16_fp8 v204, v136, 1.0
	v_cvt_scalef32_pk_bf16_fp8 v205, v136, 1.0 op_sel:[1,0,0]
	v_cvt_scalef32_pk_bf16_fp8 v207, v137, 1.0 op_sel:[1,0,0]
	v_cvt_scalef32_pk_bf16_fp8 v208, v138, 1.0
	v_cvt_scalef32_pk_bf16_fp8 v209, v138, 1.0 op_sel:[1,0,0]
	v_cvt_scalef32_pk_bf16_fp8 v211, v139, 1.0
	v_cvt_scalef32_pk_bf16_fp8 v219, v139, 1.0 op_sel:[1,0,0]
	v_dot2_f32_bf16 v220, v204, v72, 0
	v_dot2_f32_bf16 v220, v205, v73, v220
	v_dot2_f32_bf16 v220, v206, v74, v220
	v_dot2_f32_bf16 v220, v207, v75, v220
	v_dot2_f32_bf16 v220, v208, v140, v220
	v_dot2_f32_bf16 v220, v209, v141, v220
	v_dot2_f32_bf16 v220, v211, v142, v220
	v_dot2_f32_bf16 v220, v219, v143, v220
	s_nop 2
	v_cndmask_b32_e64 v206, v213, v217, s[8:9]
	ds_bpermute_b32 v206, v193, v206
	v_cndmask_b32_e64 v207, v214, v218, s[8:9]
	v_cndmask_b32_e64 v210, v212, v216, s[8:9]
	ds_bpermute_b32 v207, v193, v207
	v_cndmask_b32_e64 v208, v215, v220, s[8:9]
	ds_bpermute_b32 v210, v193, v210
	ds_bpermute_b32 v208, v193, v208
	v_cndmask_b32_e64 v205, v217, v213, s[8:9]
	s_waitcnt lgkmcnt(3)
	v_add_f32_e32 v205, v205, v206
	v_cndmask_b32_e64 v206, v218, v214, s[8:9]
	v_cndmask_b32_e64 v204, v216, v212, s[8:9]
	s_waitcnt lgkmcnt(2)
	v_add_f32_e32 v206, v206, v207
	v_cndmask_b32_e64 v207, v220, v215, s[8:9]
	s_waitcnt lgkmcnt(1)
	v_add_f32_e32 v204, v204, v210
	s_waitcnt lgkmcnt(0)
	v_add_f32_e32 v207, v207, v208
	v_cndmask_b32_e64 v208, v204, v206, s[10:11]
	v_cndmask_b32_e64 v209, v205, v207, s[10:11]
	ds_bpermute_b32 v208, v194, v208
	ds_bpermute_b32 v209, v194, v209
	v_cndmask_b32_e64 v204, v206, v204, s[10:11]
	v_cndmask_b32_e64 v205, v207, v205, s[10:11]
	v_cndmask_b32_e64 v203, v183, v202, s[12:13]
	s_waitcnt lgkmcnt(1)
	v_add_f32_e32 v204, v204, v208
	s_waitcnt lgkmcnt(0)
	v_add_f32_e32 v205, v205, v209
	ds_bpermute_b32 v203, v195, v203
	v_cndmask_b32_e64 v206, v204, v205, s[12:13]
	ds_bpermute_b32 v206, v195, v206
	v_cndmask_b32_e64 v183, v202, v183, s[12:13]
	s_waitcnt lgkmcnt(1)
	v_add_f32_e32 v207, v183, v203
	v_cndmask_b32_e64 v183, v205, v204, s[12:13]
	s_waitcnt lgkmcnt(0)
	v_add_f32_e32 v204, v183, v206
	s_setprio 0
	v_ashrrev_i32_e32 v183, 31, v182
	v_lshlrev_b64 v[202:203], 12, v[182:183]
	v_lshl_add_u64 v[202:203], v[178:179], 0, v[202:203]
	global_store_dword v[202:203], v207, off
	global_store_dword v[202:203], v204, off offset:256
	s_and_saveexec_b64 s[36:37], s[14:15]
	s_cbranch_execz .LBB0_1228
	v_mov_b64_e32 v[142:143], v[70:71]
	v_mov_b64_e32 v[74:75], v[66:67]
	v_mov_b64_e32 v[140:141], v[68:69]
	v_mov_b64_e32 v[72:73], v[64:65]
	s_and_saveexec_b64 s[0:1], s[16:17]
	s_cbranch_execz .LBB0_1236
	ds_bpermute_b32 v72, v149, v201
	ds_bpermute_b32 v74, v151, v201
	ds_bpermute_b32 v84, v187, v201
	ds_bpermute_b32 v86, v188, v201
	ds_bpermute_b32 v92, v189, v201
	s_waitcnt lgkmcnt(4)
	ds_bpermute_b32 v94, v190, v201
	s_waitcnt lgkmcnt(4)
	v_lshl_add_u32 v72, v72, 7, v252
	ds_bpermute_b32 v100, v191, v201
	v_lshl_add_u32 v74, v74, 7, v252
	s_waitcnt lgkmcnt(4)
	ds_bpermute_b32 v102, v198, v201
	global_load_dwordx4 v[76:79], v72, s[98:99]
	global_load_dwordx4 v[80:83], v74, s[98:99]
	v_lshl_add_u32 v72, v84, 7, v252
	s_waitcnt lgkmcnt(4)
	ds_bpermute_b32 v108, v149, v185
	v_lshl_add_u32 v74, v86, 7, v252
	s_waitcnt lgkmcnt(4)
	ds_bpermute_b32 v110, v151, v185
	global_load_dwordx4 v[84:87], v72, s[98:99]
	global_load_dwordx4 v[88:91], v74, s[98:99]
	v_lshl_add_u32 v72, v92, 7, v252
	s_waitcnt lgkmcnt(4)
	ds_bpermute_b32 v116, v187, v185
	v_lshl_add_u32 v74, v94, 7, v252
	s_waitcnt lgkmcnt(4)
	ds_bpermute_b32 v118, v188, v185
	global_load_dwordx4 v[92:95], v72, s[98:99]
	global_load_dwordx4 v[96:99], v74, s[98:99]
	v_lshl_add_u32 v72, v100, 7, v252
	s_waitcnt lgkmcnt(4)
	ds_bpermute_b32 v124, v189, v185
	v_lshl_add_u32 v74, v102, 7, v252
	s_waitcnt lgkmcnt(4)
	ds_bpermute_b32 v126, v190, v185
	global_load_dwordx4 v[100:103], v72, s[98:99]
	global_load_dwordx4 v[104:107], v74, s[98:99]
	v_lshl_add_u32 v72, v108, 7, v252
	s_waitcnt lgkmcnt(4)
	ds_bpermute_b32 v132, v191, v185
	v_lshl_add_u32 v74, v110, 7, v252
	s_waitcnt lgkmcnt(4)
	ds_bpermute_b32 v134, v198, v185
	global_load_dwordx4 v[108:111], v72, s[98:99]
	global_load_dwordx4 v[112:115], v74, s[98:99]
	v_lshl_add_u32 v72, v116, 7, v252
	s_waitcnt lgkmcnt(4)
	v_lshl_add_u32 v74, v118, 7, v252
	s_waitcnt lgkmcnt(3)
	global_load_dwordx4 v[116:119], v72, s[98:99]
	global_load_dwordx4 v[120:123], v74, s[98:99]
	v_lshl_add_u32 v72, v124, 7, v252
	s_waitcnt lgkmcnt(2)
	v_lshl_add_u32 v74, v126, 7, v252
	s_waitcnt lgkmcnt(1)
	global_load_dwordx4 v[124:127], v72, s[98:99]
	global_load_dwordx4 v[128:131], v74, s[98:99]
	v_lshl_add_u32 v72, v132, 7, v252
	s_waitcnt lgkmcnt(0)
	v_lshl_add_u32 v74, v134, 7, v252
	v_ashrrev_i32_e32 v185, 31, v184
	global_load_dwordx4 v[132:135], v72, s[98:99]
	global_load_dwordx4 v[136:139], v74, s[98:99]
	v_lshlrev_b64 v[72:73], 11, v[184:185]
	v_lshl_add_u64 v[72:73], v[168:169], 0, v[72:73]
	global_load_dwordx4 v[140:143], v[72:73], off offset:16
	s_nop 0
	global_load_dwordx4 v[72:75], v[72:73], off

; DI float gelu_exact(float v) { return 0.5f * v * (1.0f + erff(v * 0.70710678118654752f)); }
; DI void peer_hw_phase(const float* __restrict__ ph, const int* __restrict__ eidx, const float* __restrict__ su, const float* __restrict__ sv, float* __restrict__ gws) {
;     const size_t n = (size_t)T_TOK * 128, nthreads = (size_t)gridDim.x * blockDim.x;
;     for (size_t i = (size_t)blockIdx.x * blockDim.x + threadIdx.x; i < n; i += nthreads) {
;         float hsum = 0.f;
; #pragma unroll
;         for (int j = 0; j < 8; ++j) hsum += ph[(size_t)j * n + i];
;         const int e = eidx[i];
;         gws[i] = gws[i] * gelu_exact(hsum * su[e]) * sv[e];
;     }
; }
.LBB0_1290:
	s_or_b64 exec, exec, s[0:1]
	s_waitcnt lgkmcnt(0)
	s_barrier
	s_mov_b64 s[0:1], exec
	v_readlane_b32 s2, v253, 3
	v_readlane_b32 s3, v253, 4
	s_and_b64 s[2:3], s[0:1], s[2:3]
	s_mov_b64 exec, s[2:3]
	s_cbranch_execz .LBB0_1297
	s_add_u32 s2, s90, 0x3d410000
	s_addc_u32 s3, s91, 0
	s_add_u32 s6, s90, 0x3d430000
	s_addc_u32 s7, s91, 0
	s_lshl_b64 s[8:9], s[34:35], 2
	v_lshrrev_b32_e32 v18, 7, v176
	v_lshlrev_b32_e32 v18, 12, v18
	v_and_b32_e32 v19, 0x7f, v176
	v_lshl_or_b32 v18, v19, 2, v18
	v_mov_b32_e32 v19, 0
	v_lshl_add_u64 v[18:19], v[18:19], 0, s[90:91]
	s_lshl_b64 s[96:97], s[34:35], 5
	s_mov_b64 s[10:11], 0
	s_mov_b64 s[12:13], 0x32000000
	s_mov_b32 s18, 0x378e98ab
	s_mov_b32 s19, 0x3b7cd369
	s_mov_b32 s20, 0xbcc618b2
	s_mov_b32 s21, 0x3dda74e4
	s_mov_b32 s22, 0x3f228afd
	s_mov_b32 s23, 0x3e03c728
	s_mov_b32 s24, 0xbfb8aa3b
	s_mov_b32 s25, 0x42ce8ed0
	s_mov_b32 s27, 0xc2b17218
	v_mov_b32_e32 v2, 0x3ba10414
	s_brev_b32 s28, -2
	s_mov_b64 s[14:15], 0x7fffff
	v_mov_b32_e32 v3, 0xb9c68948
	v_mov_b32_e32 v4, 0x7f800000
	s_branch .LBB0_1293
.LBB0_1292:
	s_or_b64 exec, exec, s[16:17]
	v_lshl_add_u64 v[18:19], v[18:19], 0, s[96:97]
	v_lshl_add_u64 v[0:1], v[0:1], 2, s[6:7]
	global_load_dword v9, v[0:1], off
	v_bfi_b32 v7, s28, v8, v7
	v_mul_f32_e32 v6, 0.5, v6
	v_add_f32_e32 v7, 1.0, v7
	v_lshl_add_u64 v[176:177], v[176:177], 0, s[34:35]
	v_mul_f32_e32 v6, v6, v7
	v_cmp_lt_u64_e32 vcc, s[14:15], v[176:177]
	s_waitcnt vmcnt(1)
	v_mul_f32_e32 v5, v5, v6
	v_lshl_add_u64 v[0:1], v[144:145], 0, s[12:13]
	s_or_b64 s[10:11], vcc, s[10:11]
	v_lshl_add_u64 v[144:145], v[144:145], 0, s[8:9]
	s_waitcnt vmcnt(0)
	v_mul_f32_e32 v5, v9, v5
	global_store_dword v[0:1], v5, off
	s_andn2_b64 exec, exec, s[10:11]
	s_cbranch_execz .LBB0_1297
.LBB0_1293:
	v_add_co_u32_e32 v0, vcc, 0x30000000, v144
	s_nop 1
	v_addc_co_u32_e32 v1, vcc, 0, v145, vcc
	global_load_dword v0, v[0:1], off
	s_nop 0
	global_load_dword v20, v[18:19], off
	global_load_dword v21, v[18:19], off offset:512
	global_load_dword v22, v[18:19], off offset:1024
	global_load_dword v10, v[18:19], off offset:1536
	global_load_dword v11, v[18:19], off offset:2048
	global_load_dword v12, v[18:19], off offset:2560
	global_load_dword v13, v[18:19], off offset:3072
	global_load_dword v14, v[18:19], off offset:3584
	v_add_co_u32_e32 v6, vcc, 0x32000000, v144
	s_waitcnt vmcnt(8)
	v_ashrrev_i32_e32 v1, 31, v0
	v_lshl_add_u64 v[8:9], v[0:1], 2, s[2:3]
	global_load_dword v8, v[8:9], off
	v_addc_co_u32_e32 v7, vcc, 0, v145, vcc
	global_load_dword v5, v[6:7], off
	s_waitcnt vmcnt(9)
	v_add_f32_e32 v6, 0, v20
	s_waitcnt vmcnt(8)
	v_add_f32_e32 v6, v6, v21
	s_waitcnt vmcnt(7)
	v_add_f32_e32 v6, v6, v22
	s_waitcnt vmcnt(6)
	v_add_f32_e32 v6, v6, v10
	s_waitcnt vmcnt(5)
	v_add_f32_e32 v6, v6, v11
	s_waitcnt vmcnt(4)
	v_add_f32_e32 v6, v6, v12
	s_waitcnt vmcnt(3)
	v_add_f32_e32 v6, v6, v13
	s_waitcnt vmcnt(2)
	v_add_f32_e32 v6, v6, v14
	s_waitcnt vmcnt(1)
	v_mul_f32_e32 v6, v6, v8
	v_mul_f32_e32 v7, 0x3f3504f3, v6
	v_cmp_nlt_f32_e64 s[16:17], |v7|, 1.0
	s_and_saveexec_b64 s[36:37], s[16:17]
	s_xor_b64 s[16:17], exec, s[36:37]
	s_cbranch_execz .LBB0_1295
	v_fma_f32 v8, |v7|, s18, v3
	v_fma_f32 v8, |v7|, v8, s19
	v_fma_f32 v8, |v7|, v8, s20
	v_fma_f32 v8, |v7|, v8, s21
	v_fma_f32 v8, |v7|, v8, s22
	v_fma_f32 v8, |v7|, v8, s23
	v_fma_f32 v8, |v7|, v8, |v7|
	v_mul_f32_e32 v9, 0xbfb8aa3b, v8
	v_fma_f32 v10, v8, s24, -v9
	v_rndne_f32_e32 v11, v9
	v_fmac_f32_e32 v10, 0xb2a5705f, v8
	v_sub_f32_e32 v9, v9, v11
	v_add_f32_e32 v9, v9, v10
	v_cvt_i32_f32_e32 v10, v11
	v_exp_f32_e32 v9, v9
	v_cmp_nlt_f32_e32 vcc, s25, v8
	v_ldexp_f32 v9, v9, v10
	s_nop 0
	v_cndmask_b32_e32 v9, 0, v9, vcc
	v_cmp_ngt_f32_e32 vcc, s27, v8
	s_nop 1
	v_cndmask_b32_e32 v8, v4, v9, vcc
	v_sub_f32_e32 v8, 1.0, v8
